# G1/G3/G5/G7: the two wave-halves run their tile epilogues un-aligned (leading half's pre-epilogue barrier and trailing half's post-epilogue barrier dropped, one balancing barrier before the drain)
# baseline (speedup 1.0000x reference)
.LBB0_157:
	ds_read_b128 v[154:157], v151
	ds_read_b128 v[158:161], v151 offset:1024
	ds_read_b128 v[162:165], v151 offset:2048
	ds_read_b128 v[166:169], v151 offset:3072
	ds_read_b128 v[170:173], v152
	ds_read_b128 v[174:177], v152 offset:1024
	ds_read_b128 v[178:181], v152 offset:2048
	ds_read_b128 v[182:185], v152 offset:3072
	s_add_u32 s8, s26, 0xfffc0080
	s_addc_u32 s9, s27, -1
	s_cmp_eq_u32 s45, 12
	s_cselect_b32 s29, s13, s9
	s_cselect_b32 s28, s39, s8
	s_cselect_b32 s9, s11, s44
	s_cselect_b32 s8, s40, s41
	v_lshl_add_u64 v[144:145], s[26:27], 0, v[136:137]
	s_add_i32 m0, s16, 0xc000
	ds_read_b128 v[186:189], v153
	ds_read_b128 v[190:193], v153 offset:1024
	ds_read_b128 v[196:199], v153 offset:2048
	ds_read_b128 v[200:203], v153 offset:3072
	ds_read_b128 v[204:207], v153 offset:4096
	ds_read_b128 v[208:211], v153 offset:5120
	ds_read_b128 v[212:215], v153 offset:6144
	ds_read_b128 v[216:219], v153 offset:7168
	global_load_lds_dwordx4 v[144:145], off
	v_lshl_add_u64 v[144:145], s[26:27], 0, v[138:139]
	s_add_i32 m0, s16, 0xe000
	s_nop 0
	global_load_lds_dwordx4 v[144:145], off
	s_waitcnt vmcnt(8)
	s_waitcnt lgkmcnt(0)
	s_barrier
	s_setprio 1
	s_waitcnt lgkmcnt(0)
	v_mfma_f32_16x16x32_bf16 v[124:127], v[154:157], v[186:189], v[124:127]
	v_mfma_f32_16x16x32_bf16 v[120:123], v[162:165], v[186:189], v[120:123]
	v_mfma_f32_16x16x32_bf16 v[116:119], v[154:157], v[196:199], v[116:119]
	v_mfma_f32_16x16x32_bf16 v[108:111], v[162:165], v[196:199], v[108:111]
	v_mfma_f32_16x16x32_bf16 v[96:99], v[154:157], v[204:207], v[96:99]
	v_mfma_f32_16x16x32_bf16 v[88:91], v[162:165], v[204:207], v[88:91]
	v_mfma_f32_16x16x32_bf16 v[84:87], v[154:157], v[212:215], v[84:87]
	v_mfma_f32_16x16x32_bf16 v[76:79], v[162:165], v[212:215], v[76:79]
	v_mfma_f32_16x16x32_bf16 v[124:127], v[158:161], v[190:193], v[124:127]
	v_mfma_f32_16x16x32_bf16 v[120:123], v[166:169], v[190:193], v[120:123]
	v_mfma_f32_16x16x32_bf16 v[116:119], v[158:161], v[200:203], v[116:119]
	v_mfma_f32_16x16x32_bf16 v[108:111], v[166:169], v[200:203], v[108:111]
	v_mfma_f32_16x16x32_bf16 v[96:99], v[158:161], v[208:211], v[96:99]
	v_mfma_f32_16x16x32_bf16 v[88:91], v[166:169], v[208:211], v[88:91]
	v_mfma_f32_16x16x32_bf16 v[84:87], v[158:161], v[216:219], v[84:87]
	v_mfma_f32_16x16x32_bf16 v[76:79], v[166:169], v[216:219], v[76:79]
	s_setprio 0
	s_setprio 1
	v_mfma_f32_16x16x32_bf16 v[112:115], v[170:173], v[186:189], v[112:115]
	v_mfma_f32_16x16x32_bf16 v[104:107], v[178:181], v[186:189], v[104:107]
	v_mfma_f32_16x16x32_bf16 v[100:103], v[170:173], v[196:199], v[100:103]
	v_mfma_f32_16x16x32_bf16 v[92:95], v[178:181], v[196:199], v[92:95]
	v_mfma_f32_16x16x32_bf16 v[80:83], v[170:173], v[204:207], v[80:83]
	v_mfma_f32_16x16x32_bf16 v[72:75], v[178:181], v[204:207], v[72:75]
	v_mfma_f32_16x16x32_bf16 v[68:71], v[170:173], v[212:215], v[68:71]
	v_mfma_f32_16x16x32_bf16 v[64:67], v[178:181], v[212:215], v[64:67]
	v_mfma_f32_16x16x32_bf16 v[112:115], v[174:177], v[190:193], v[112:115]
	v_mfma_f32_16x16x32_bf16 v[104:107], v[182:185], v[190:193], v[104:107]
	v_mfma_f32_16x16x32_bf16 v[100:103], v[174:177], v[200:203], v[100:103]
	v_mfma_f32_16x16x32_bf16 v[92:95], v[182:185], v[200:203], v[92:95]
	v_mfma_f32_16x16x32_bf16 v[80:83], v[174:177], v[208:211], v[80:83]
	v_mfma_f32_16x16x32_bf16 v[72:75], v[182:185], v[208:211], v[72:75]
	v_mfma_f32_16x16x32_bf16 v[68:71], v[174:177], v[216:219], v[68:71]
	v_mfma_f32_16x16x32_bf16 v[64:67], v[182:185], v[216:219], v[64:67]
	s_setprio 0
	s_barrier
	s_add_i32 s46, s31, s3
	v_lshl_add_u64 v[144:145], s[8:9], 0, v[132:133]
	s_mov_b32 m0, s46
	ds_read_b128 v[186:189], v153 offset:16384
	ds_read_b128 v[190:193], v153 offset:17408
	ds_read_b128 v[196:199], v153 offset:18432
	ds_read_b128 v[200:203], v153 offset:19456
	ds_read_b128 v[204:207], v153 offset:20480
	ds_read_b128 v[208:211], v153 offset:21504
	ds_read_b128 v[212:215], v153 offset:22528
	ds_read_b128 v[216:219], v153 offset:23552
	global_load_lds_dwordx4 v[144:145], off
	s_add_i32 m0, s46, 0x2000
	s_add_u32 s46, s8, 0x40000
	v_lshl_add_u64 v[220:221], s[8:9], 0, v[128:129]
	s_addc_u32 s47, s9, 0
	s_add_i32 s48, s33, s3
	global_load_lds_dwordx4 v[220:221], off
	v_lshl_add_u64 v[222:223], s[46:47], 0, v[132:133]
	s_mov_b32 m0, s48
	v_lshl_add_u64 v[224:225], s[28:29], 0, v[130:131]
	global_load_lds_dwordx4 v[222:223], off
	v_lshl_add_u64 v[222:223], s[46:47], 0, v[128:129]
	s_add_i32 m0, s48, 0x2000
	s_nop 0
	global_load_lds_dwordx4 v[222:223], off
	v_lshl_add_u64 v[222:223], s[28:29], 0, v[134:135]
	s_mov_b32 m0, s16
	s_nop 0
	global_load_lds_dwordx4 v[222:223], off
	s_mov_b32 m0, s17
	s_nop 0
	global_load_lds_dwordx4 v[224:225], off
	s_waitcnt vmcnt(8)
	s_waitcnt lgkmcnt(0)
	s_barrier
	s_setprio 1
	s_waitcnt lgkmcnt(0)
	v_mfma_f32_16x16x32_bf16 v[60:63], v[154:157], v[186:189], v[60:63]
	v_mfma_f32_16x16x32_bf16 v[56:59], v[162:165], v[186:189], v[56:59]
	v_mfma_f32_16x16x32_bf16 v[52:55], v[154:157], v[196:199], v[52:55]
	v_mfma_f32_16x16x32_bf16 v[44:47], v[162:165], v[196:199], v[44:47]
	v_mfma_f32_16x16x32_bf16 v[32:35], v[154:157], v[204:207], v[32:35]
	v_mfma_f32_16x16x32_bf16 v[24:27], v[162:165], v[204:207], v[24:27]
	v_mfma_f32_16x16x32_bf16 v[20:23], v[154:157], v[212:215], v[20:23]
	v_mfma_f32_16x16x32_bf16 v[12:15], v[162:165], v[212:215], v[12:15]
	v_mfma_f32_16x16x32_bf16 v[60:63], v[158:161], v[190:193], v[60:63]
	v_mfma_f32_16x16x32_bf16 v[56:59], v[166:169], v[190:193], v[56:59]
	v_mfma_f32_16x16x32_bf16 v[52:55], v[158:161], v[200:203], v[52:55]
	v_mfma_f32_16x16x32_bf16 v[44:47], v[166:169], v[200:203], v[44:47]
	v_mfma_f32_16x16x32_bf16 v[32:35], v[158:161], v[208:211], v[32:35]
	v_mfma_f32_16x16x32_bf16 v[24:27], v[166:169], v[208:211], v[24:27]
	v_mfma_f32_16x16x32_bf16 v[20:23], v[158:161], v[216:219], v[20:23]
	v_mfma_f32_16x16x32_bf16 v[12:15], v[166:169], v[216:219], v[12:15]
	s_setprio 0
	s_setprio 1
	v_mfma_f32_16x16x32_bf16 v[48:51], v[170:173], v[186:189], v[48:51]
	v_mfma_f32_16x16x32_bf16 v[40:43], v[178:181], v[186:189], v[40:43]
	v_mfma_f32_16x16x32_bf16 v[36:39], v[170:173], v[196:199], v[36:39]
	v_mfma_f32_16x16x32_bf16 v[28:31], v[178:181], v[196:199], v[28:31]
	v_mfma_f32_16x16x32_bf16 v[16:19], v[170:173], v[204:207], v[16:19]
	v_mfma_f32_16x16x32_bf16 v[8:11], v[178:181], v[204:207], v[8:11]
	v_mfma_f32_16x16x32_bf16 v[4:7], v[170:173], v[212:215], v[4:7]
	v_mfma_f32_16x16x32_bf16 v[0:3], v[178:181], v[212:215], v[0:3]
	v_mfma_f32_16x16x32_bf16 v[48:51], v[174:177], v[190:193], v[48:51]
	v_mfma_f32_16x16x32_bf16 v[40:43], v[182:185], v[190:193], v[40:43]
	v_mfma_f32_16x16x32_bf16 v[36:39], v[174:177], v[200:203], v[36:39]
	v_mfma_f32_16x16x32_bf16 v[28:31], v[182:185], v[200:203], v[28:31]
	v_mfma_f32_16x16x32_bf16 v[16:19], v[174:177], v[208:211], v[16:19]
	v_mfma_f32_16x16x32_bf16 v[8:11], v[182:185], v[208:211], v[8:11]
	v_mfma_f32_16x16x32_bf16 v[4:7], v[174:177], v[216:219], v[4:7]
	v_mfma_f32_16x16x32_bf16 v[0:3], v[182:185], v[216:219], v[0:3]
	s_setprio 0
	s_barrier
	s_add_i32 s46, 0, 0x18000
	s_add_i32 s47, 0, 0x1c000
	v_add_u32_e32 v166, s46, v148
	v_add_u32_e32 v182, s47, v148
	ds_read_b128 v[154:157], v166
	ds_read_b128 v[158:161], v166 offset:1024
	ds_read_b128 v[162:165], v166 offset:2048
	ds_read_b128 v[166:169], v166 offset:3072
	ds_read_b128 v[170:173], v182
	ds_read_b128 v[174:177], v182 offset:1024
	ds_read_b128 v[178:181], v182 offset:2048
	ds_read_b128 v[182:185], v182 offset:3072
	s_add_u32 s28, s28, 0x40000
	s_addc_u32 s29, s29, 0
	s_mov_b32 m0, s18
	v_lshl_add_u64 v[226:227], s[28:29], 0, v[134:135]
	ds_read_b128 v[186:189], v153 offset:32768
	ds_read_b128 v[190:193], v153 offset:33792
	ds_read_b128 v[196:199], v153 offset:34816
	ds_read_b128 v[200:203], v153 offset:35840
	ds_read_b128 v[204:207], v153 offset:36864
	ds_read_b128 v[208:211], v153 offset:37888
	ds_read_b128 v[212:215], v153 offset:38912
	ds_read_b128 v[216:219], v153 offset:39936
	global_load_lds_dwordx4 v[226:227], off
	v_lshl_add_u64 v[226:227], s[28:29], 0, v[130:131]
	s_mov_b32 m0, s19
	s_nop 0
	global_load_lds_dwordx4 v[226:227], off
	s_waitcnt vmcnt(8)
	s_waitcnt lgkmcnt(0)
	s_barrier
	s_setprio 1
	s_waitcnt lgkmcnt(0)
	v_mfma_f32_16x16x32_bf16 v[124:127], v[154:157], v[186:189], v[124:127]
	v_mfma_f32_16x16x32_bf16 v[120:123], v[162:165], v[186:189], v[120:123]
	v_mfma_f32_16x16x32_bf16 v[116:119], v[154:157], v[196:199], v[116:119]
	v_mfma_f32_16x16x32_bf16 v[108:111], v[162:165], v[196:199], v[108:111]
	v_mfma_f32_16x16x32_bf16 v[96:99], v[154:157], v[204:207], v[96:99]
	v_mfma_f32_16x16x32_bf16 v[88:91], v[162:165], v[204:207], v[88:91]
	v_mfma_f32_16x16x32_bf16 v[84:87], v[154:157], v[212:215], v[84:87]
	v_mfma_f32_16x16x32_bf16 v[76:79], v[162:165], v[212:215], v[76:79]
	v_mfma_f32_16x16x32_bf16 v[124:127], v[158:161], v[190:193], v[124:127]
	v_mfma_f32_16x16x32_bf16 v[120:123], v[166:169], v[190:193], v[120:123]
	v_mfma_f32_16x16x32_bf16 v[116:119], v[158:161], v[200:203], v[116:119]
	v_mfma_f32_16x16x32_bf16 v[108:111], v[166:169], v[200:203], v[108:111]
	v_mfma_f32_16x16x32_bf16 v[96:99], v[158:161], v[208:211], v[96:99]
	v_mfma_f32_16x16x32_bf16 v[88:91], v[166:169], v[208:211], v[88:91]
	v_mfma_f32_16x16x32_bf16 v[84:87], v[158:161], v[216:219], v[84:87]
	v_mfma_f32_16x16x32_bf16 v[76:79], v[166:169], v[216:219], v[76:79]
	s_setprio 0
	s_setprio 1
	v_mfma_f32_16x16x32_bf16 v[112:115], v[170:173], v[186:189], v[112:115]
	v_mfma_f32_16x16x32_bf16 v[104:107], v[178:181], v[186:189], v[104:107]
	v_mfma_f32_16x16x32_bf16 v[100:103], v[170:173], v[196:199], v[100:103]
	v_mfma_f32_16x16x32_bf16 v[92:95], v[178:181], v[196:199], v[92:95]
	v_mfma_f32_16x16x32_bf16 v[80:83], v[170:173], v[204:207], v[80:83]
	v_mfma_f32_16x16x32_bf16 v[72:75], v[178:181], v[204:207], v[72:75]
	v_mfma_f32_16x16x32_bf16 v[68:71], v[170:173], v[212:215], v[68:71]
	v_mfma_f32_16x16x32_bf16 v[64:67], v[178:181], v[212:215], v[64:67]
	v_mfma_f32_16x16x32_bf16 v[112:115], v[174:177], v[190:193], v[112:115]
	v_mfma_f32_16x16x32_bf16 v[104:107], v[182:185], v[190:193], v[104:107]
	v_mfma_f32_16x16x32_bf16 v[100:103], v[174:177], v[200:203], v[100:103]
	v_mfma_f32_16x16x32_bf16 v[92:95], v[182:185], v[200:203], v[92:95]
	v_mfma_f32_16x16x32_bf16 v[80:83], v[174:177], v[208:211], v[80:83]
	v_mfma_f32_16x16x32_bf16 v[72:75], v[182:185], v[208:211], v[72:75]
	v_mfma_f32_16x16x32_bf16 v[68:71], v[174:177], v[216:219], v[68:71]
	v_mfma_f32_16x16x32_bf16 v[64:67], v[182:185], v[216:219], v[64:67]
	s_setprio 0
	s_barrier
	s_add_i32 s28, s46, s3
	v_lshl_add_u64 v[144:145], v[144:145], 0, s[4:5]
	s_mov_b32 m0, s28
	ds_read_b128 v[186:189], v153 offset:49152
	ds_read_b128 v[190:193], v153 offset:50176
	ds_read_b128 v[196:199], v153 offset:51200
	ds_read_b128 v[200:203], v153 offset:52224
	ds_read_b128 v[204:207], v153 offset:53248
	ds_read_b128 v[208:211], v153 offset:54272
	ds_read_b128 v[212:215], v153 offset:55296
	ds_read_b128 v[216:219], v153 offset:56320
	global_load_lds_dwordx4 v[144:145], off
	s_add_i32 m0, s28, 0x2000
	s_add_u32 s8, s8, 0x40080
	v_lshl_add_u64 v[144:145], v[220:221], 0, s[4:5]
	s_addc_u32 s9, s9, 0
	s_add_i32 s28, s47, s3
	global_load_lds_dwordx4 v[144:145], off
	v_lshl_add_u64 v[144:145], s[8:9], 0, v[132:133]
	s_mov_b32 m0, s28
	s_nop 0
	global_load_lds_dwordx4 v[144:145], off
	v_lshl_add_u64 v[144:145], s[8:9], 0, v[128:129]
	s_add_i32 m0, s28, 0x2000
	s_nop 0
	global_load_lds_dwordx4 v[144:145], off
	v_lshl_add_u64 v[144:145], v[222:223], 0, s[4:5]
	s_mov_b32 m0, s25
	s_nop 0
	global_load_lds_dwordx4 v[144:145], off
	v_lshl_add_u64 v[144:145], v[224:225], 0, s[4:5]
	s_mov_b32 m0, s30
	s_nop 0
	global_load_lds_dwordx4 v[144:145], off
	s_waitcnt vmcnt(8)
	s_waitcnt lgkmcnt(0)
	s_barrier
	s_setprio 1
	s_waitcnt lgkmcnt(0)
	v_mfma_f32_16x16x32_bf16 v[60:63], v[154:157], v[186:189], v[60:63]
	v_mfma_f32_16x16x32_bf16 v[56:59], v[162:165], v[186:189], v[56:59]
	v_mfma_f32_16x16x32_bf16 v[52:55], v[154:157], v[196:199], v[52:55]
	v_mfma_f32_16x16x32_bf16 v[44:47], v[162:165], v[196:199], v[44:47]
	v_mfma_f32_16x16x32_bf16 v[32:35], v[154:157], v[204:207], v[32:35]
	v_mfma_f32_16x16x32_bf16 v[24:27], v[162:165], v[204:207], v[24:27]
	v_mfma_f32_16x16x32_bf16 v[20:23], v[154:157], v[212:215], v[20:23]
	v_mfma_f32_16x16x32_bf16 v[12:15], v[162:165], v[212:215], v[12:15]
	v_mfma_f32_16x16x32_bf16 v[60:63], v[158:161], v[190:193], v[60:63]
	v_mfma_f32_16x16x32_bf16 v[56:59], v[166:169], v[190:193], v[56:59]
	v_mfma_f32_16x16x32_bf16 v[52:55], v[158:161], v[200:203], v[52:55]
	v_mfma_f32_16x16x32_bf16 v[44:47], v[166:169], v[200:203], v[44:47]
	v_mfma_f32_16x16x32_bf16 v[32:35], v[158:161], v[208:211], v[32:35]
	v_mfma_f32_16x16x32_bf16 v[24:27], v[166:169], v[208:211], v[24:27]
	v_mfma_f32_16x16x32_bf16 v[20:23], v[158:161], v[216:219], v[20:23]
	v_mfma_f32_16x16x32_bf16 v[12:15], v[166:169], v[216:219], v[12:15]
	s_setprio 0
	s_setprio 1
	v_mfma_f32_16x16x32_bf16 v[48:51], v[170:173], v[186:189], v[48:51]
	v_mfma_f32_16x16x32_bf16 v[40:43], v[178:181], v[186:189], v[40:43]
	v_mfma_f32_16x16x32_bf16 v[36:39], v[170:173], v[196:199], v[36:39]
	v_mfma_f32_16x16x32_bf16 v[28:31], v[178:181], v[196:199], v[28:31]
	v_mfma_f32_16x16x32_bf16 v[16:19], v[170:173], v[204:207], v[16:19]
	v_mfma_f32_16x16x32_bf16 v[8:11], v[178:181], v[204:207], v[8:11]
	v_mfma_f32_16x16x32_bf16 v[4:7], v[170:173], v[212:215], v[4:7]
	v_mfma_f32_16x16x32_bf16 v[0:3], v[178:181], v[212:215], v[0:3]
	v_mfma_f32_16x16x32_bf16 v[48:51], v[174:177], v[190:193], v[48:51]
	v_mfma_f32_16x16x32_bf16 v[40:43], v[182:185], v[190:193], v[40:43]
	v_mfma_f32_16x16x32_bf16 v[36:39], v[174:177], v[200:203], v[36:39]
	v_mfma_f32_16x16x32_bf16 v[28:31], v[182:185], v[200:203], v[28:31]
	v_mfma_f32_16x16x32_bf16 v[16:19], v[174:177], v[208:211], v[16:19]
	v_mfma_f32_16x16x32_bf16 v[8:11], v[182:185], v[208:211], v[8:11]
	v_mfma_f32_16x16x32_bf16 v[4:7], v[174:177], v[216:219], v[4:7]
	v_mfma_f32_16x16x32_bf16 v[0:3], v[182:185], v[216:219], v[0:3]
	s_setprio 0
	s_barrier
	s_add_i32 s45, s45, 2
	s_add_u32 s26, s26, 0x100
	s_addc_u32 s27, s27, 0
	s_add_u32 s41, s41, 0x100
	s_addc_u32 s44, s44, 0
	s_cmp_gt_u32 s45, 13
	s_cbranch_scc0 .LBB0_157
	s_and_b64 vcc, exec, s[6:7]
	s_branch .LBB0_160
	s_barrier
.LBB0_160:
	s_cmp_lt_i32 s38, 12
	v_lshl_add_u32 v161, s37, 10, v150
	s_cselect_b32 s8, s97, s91
	ds_read2_b32 v[156:157], v161 offset1:16
	s_cselect_b32 s9, 0, -12
	v_mov_b32_e32 v145, s8
	s_movk_i32 s8, 0xc00
	s_cselect_b32 s11, s96, s90
	s_cselect_b32 s8, s8, 0x400
	s_add_i32 s9, s9, s38
	v_lshl_add_u32 v154, s9, 8, v149
	v_lshl_add_u32 v160, s24, 8, v147
	v_mov_b32_e32 v144, s11
	v_ashrrev_i32_e32 v155, 31, v154
	v_lshl_add_u64 v[144:145], v[154:155], 1, v[144:145]
	v_mad_i64_i32 v[154:155], s[26:27], s8, v160, 0
	s_waitcnt lgkmcnt(0)
	v_pk_mul_f32 v[126:127], v[126:127], v[156:157] op_sel_hi:[1,0]
	v_pk_mul_f32 v[124:125], v[124:125], v[156:157] op_sel_hi:[1,0]
	v_pk_mul_f32 v[158:159], v[122:123], v[156:157] op_sel_hi:[1,0]
	v_pk_mul_f32 v[122:123], v[120:121], v[156:157] op_sel_hi:[1,0]
	v_lshl_add_u64 v[154:155], v[154:155], 1, v[144:145]
	v_cvt_pk_bf16_f32 v120, v124, v125
	v_cvt_pk_bf16_f32 v121, v126, v127
	v_cvt_pk_bf16_f32 v122, v122, v123
	v_cvt_pk_bf16_f32 v123, v158, v159
	global_store_dwordx4 v[154:155], v[120:123], off
	v_pk_mul_f32 v[114:115], v[114:115], v[156:157] op_sel_hi:[1,0]
	v_pk_mul_f32 v[112:113], v[112:113], v[156:157] op_sel_hi:[1,0]
	v_pk_mul_f32 v[120:121], v[106:107], v[156:157] op_sel_hi:[1,0]
	v_pk_mul_f32 v[106:107], v[104:105], v[156:157] op_sel_hi:[1,0]
	v_cvt_pk_bf16_f32 v104, v112, v113
	v_cvt_pk_bf16_f32 v105, v114, v115
	v_cvt_pk_bf16_f32 v106, v106, v107
	v_cvt_pk_bf16_f32 v107, v120, v121
	global_store_dwordx4 v[154:155], v[104:107], off offset:256
	v_mov_b32_e32 v114, v157
	v_pk_mul_f32 v[110:111], v[110:111], v[114:115] op_sel_hi:[1,0]
	v_or_b32_e32 v104, 16, v160
	v_mad_i64_i32 v[104:105], s[26:27], s8, v104, 0
	v_lshl_add_u64 v[112:113], v[104:105], 1, v[144:145]
	v_pk_mul_f32 v[106:107], v[118:119], v[114:115] op_sel_hi:[1,0]
	v_pk_mul_f32 v[104:105], v[116:117], v[114:115] op_sel_hi:[1,0]
	v_pk_mul_f32 v[108:109], v[108:109], v[114:115] op_sel_hi:[1,0]
	v_cvt_pk_bf16_f32 v104, v104, v105
	v_cvt_pk_bf16_f32 v105, v106, v107
	v_cvt_pk_bf16_f32 v106, v108, v109
	v_cvt_pk_bf16_f32 v107, v110, v111
	global_store_dwordx4 v[112:113], v[104:107], off
	v_pk_mul_f32 v[102:103], v[102:103], v[114:115] op_sel_hi:[1,0]
	v_pk_mul_f32 v[100:101], v[100:101], v[114:115] op_sel_hi:[1,0]
	v_pk_mul_f32 v[104:105], v[94:95], v[114:115] op_sel_hi:[1,0]
	v_pk_mul_f32 v[94:95], v[92:93], v[114:115] op_sel_hi:[1,0]
	v_cvt_pk_bf16_f32 v92, v100, v101
	v_cvt_pk_bf16_f32 v93, v102, v103
	v_cvt_pk_bf16_f32 v94, v94, v95
	v_cvt_pk_bf16_f32 v95, v104, v105
	global_store_dwordx4 v[112:113], v[92:95], off offset:256
	ds_read2_b32 v[92:93], v161 offset0:32 offset1:48
	s_andn2_b64 vcc, exec, s[42:43]
	v_or_b32_e32 v94, 32, v160
	v_mad_i64_i32 v[94:95], s[26:27], s8, v94, 0
	s_waitcnt lgkmcnt(0)
	v_pk_mul_f32 v[98:99], v[98:99], v[92:93] op_sel_hi:[1,0]
	v_pk_mul_f32 v[96:97], v[96:97], v[92:93] op_sel_hi:[1,0]
	v_pk_mul_f32 v[100:101], v[90:91], v[92:93] op_sel_hi:[1,0]
	v_pk_mul_f32 v[90:91], v[88:89], v[92:93] op_sel_hi:[1,0]
	v_lshl_add_u64 v[94:95], v[94:95], 1, v[144:145]
	v_cvt_pk_bf16_f32 v88, v96, v97
	v_cvt_pk_bf16_f32 v89, v98, v99
	v_cvt_pk_bf16_f32 v90, v90, v91
	v_cvt_pk_bf16_f32 v91, v100, v101
	global_store_dwordx4 v[94:95], v[88:91], off
	v_pk_mul_f32 v[82:83], v[82:83], v[92:93] op_sel_hi:[1,0]
	v_pk_mul_f32 v[80:81], v[80:81], v[92:93] op_sel_hi:[1,0]
	v_pk_mul_f32 v[88:89], v[74:75], v[92:93] op_sel_hi:[1,0]
	v_pk_mul_f32 v[74:75], v[72:73], v[92:93] op_sel_hi:[1,0]
	v_cvt_pk_bf16_f32 v72, v80, v81
	v_cvt_pk_bf16_f32 v73, v82, v83
	v_cvt_pk_bf16_f32 v74, v74, v75
	v_cvt_pk_bf16_f32 v75, v88, v89
	global_store_dwordx4 v[94:95], v[72:75], off offset:256
	v_mov_b32_e32 v82, v93
	v_pk_mul_f32 v[78:79], v[78:79], v[82:83] op_sel_hi:[1,0]
	v_or_b32_e32 v72, 48, v160
	v_mad_i64_i32 v[72:73], s[26:27], s8, v72, 0
	v_lshl_add_u64 v[80:81], v[72:73], 1, v[144:145]
	v_pk_mul_f32 v[74:75], v[86:87], v[82:83] op_sel_hi:[1,0]
	v_pk_mul_f32 v[72:73], v[84:85], v[82:83] op_sel_hi:[1,0]
	v_pk_mul_f32 v[76:77], v[76:77], v[82:83] op_sel_hi:[1,0]
	v_cvt_pk_bf16_f32 v72, v72, v73
	v_cvt_pk_bf16_f32 v73, v74, v75
	v_cvt_pk_bf16_f32 v74, v76, v77
	v_cvt_pk_bf16_f32 v75, v78, v79
	global_store_dwordx4 v[80:81], v[72:75], off
	v_pk_mul_f32 v[70:71], v[70:71], v[82:83] op_sel_hi:[1,0]
	v_pk_mul_f32 v[68:69], v[68:69], v[82:83] op_sel_hi:[1,0]
	v_pk_mul_f32 v[72:73], v[66:67], v[82:83] op_sel_hi:[1,0]
	v_pk_mul_f32 v[66:67], v[64:65], v[82:83] op_sel_hi:[1,0]
	v_cvt_pk_bf16_f32 v64, v68, v69
	v_cvt_pk_bf16_f32 v65, v70, v71
	v_cvt_pk_bf16_f32 v66, v66, v67
	v_cvt_pk_bf16_f32 v67, v72, v73
	global_store_dwordx4 v[80:81], v[64:67], off offset:256
	ds_read2_b32 v[64:65], v161 offset0:128 offset1:144
	s_waitcnt lgkmcnt(0)
	v_pk_mul_f32 v[62:63], v[62:63], v[64:65] op_sel_hi:[1,0]
	v_add_u32_e32 v66, 0x80, v160
	v_mad_i64_i32 v[66:67], s[26:27], s8, v66, 0
	v_pk_mul_f32 v[60:61], v[60:61], v[64:65] op_sel_hi:[1,0]
	v_pk_mul_f32 v[68:69], v[58:59], v[64:65] op_sel_hi:[1,0]
	v_pk_mul_f32 v[58:59], v[56:57], v[64:65] op_sel_hi:[1,0]
	v_lshl_add_u64 v[66:67], v[66:67], 1, v[144:145]
	v_cvt_pk_bf16_f32 v56, v60, v61
	v_cvt_pk_bf16_f32 v57, v62, v63
	v_cvt_pk_bf16_f32 v58, v58, v59
	v_cvt_pk_bf16_f32 v59, v68, v69
	global_store_dwordx4 v[66:67], v[56:59], off
	v_pk_mul_f32 v[50:51], v[50:51], v[64:65] op_sel_hi:[1,0]
	v_pk_mul_f32 v[48:49], v[48:49], v[64:65] op_sel_hi:[1,0]
	v_pk_mul_f32 v[56:57], v[42:43], v[64:65] op_sel_hi:[1,0]
	v_pk_mul_f32 v[42:43], v[40:41], v[64:65] op_sel_hi:[1,0]
	v_cvt_pk_bf16_f32 v40, v48, v49
	v_cvt_pk_bf16_f32 v41, v50, v51
	v_cvt_pk_bf16_f32 v42, v42, v43
	v_cvt_pk_bf16_f32 v43, v56, v57
	global_store_dwordx4 v[66:67], v[40:43], off offset:256
	v_mov_b32_e32 v50, v65
	v_pk_mul_f32 v[46:47], v[46:47], v[50:51] op_sel_hi:[1,0]
	v_add_u32_e32 v40, 0x90, v160
	v_mad_i64_i32 v[40:41], s[26:27], s8, v40, 0
	v_lshl_add_u64 v[48:49], v[40:41], 1, v[144:145]
	v_pk_mul_f32 v[42:43], v[54:55], v[50:51] op_sel_hi:[1,0]
	v_pk_mul_f32 v[40:41], v[52:53], v[50:51] op_sel_hi:[1,0]
	v_pk_mul_f32 v[44:45], v[44:45], v[50:51] op_sel_hi:[1,0]
	v_cvt_pk_bf16_f32 v40, v40, v41
	v_cvt_pk_bf16_f32 v41, v42, v43
	v_cvt_pk_bf16_f32 v42, v44, v45
	v_cvt_pk_bf16_f32 v43, v46, v47
	global_store_dwordx4 v[48:49], v[40:43], off
	v_pk_mul_f32 v[38:39], v[38:39], v[50:51] op_sel_hi:[1,0]
	v_pk_mul_f32 v[36:37], v[36:37], v[50:51] op_sel_hi:[1,0]
	v_pk_mul_f32 v[40:41], v[30:31], v[50:51] op_sel_hi:[1,0]
	v_pk_mul_f32 v[30:31], v[28:29], v[50:51] op_sel_hi:[1,0]
	v_cvt_pk_bf16_f32 v28, v36, v37
	v_cvt_pk_bf16_f32 v29, v38, v39
	v_cvt_pk_bf16_f32 v30, v30, v31
	v_cvt_pk_bf16_f32 v31, v40, v41
	global_store_dwordx4 v[48:49], v[28:31], off offset:256
	ds_read2_b32 v[28:29], v161 offset0:160 offset1:176
	s_waitcnt lgkmcnt(0)
	v_pk_mul_f32 v[34:35], v[34:35], v[28:29] op_sel_hi:[1,0]
	v_add_u32_e32 v30, 0xa0, v160
	v_mad_i64_i32 v[30:31], s[26:27], s8, v30, 0
	v_pk_mul_f32 v[32:33], v[32:33], v[28:29] op_sel_hi:[1,0]
	v_pk_mul_f32 v[36:37], v[26:27], v[28:29] op_sel_hi:[1,0]
	v_pk_mul_f32 v[26:27], v[24:25], v[28:29] op_sel_hi:[1,0]
	v_lshl_add_u64 v[30:31], v[30:31], 1, v[144:145]
	v_cvt_pk_bf16_f32 v24, v32, v33
	v_cvt_pk_bf16_f32 v25, v34, v35
	v_cvt_pk_bf16_f32 v26, v26, v27
	v_cvt_pk_bf16_f32 v27, v36, v37
	global_store_dwordx4 v[30:31], v[24:27], off
	v_pk_mul_f32 v[18:19], v[18:19], v[28:29] op_sel_hi:[1,0]
	v_pk_mul_f32 v[16:17], v[16:17], v[28:29] op_sel_hi:[1,0]
	v_pk_mul_f32 v[24:25], v[10:11], v[28:29] op_sel_hi:[1,0]
	v_pk_mul_f32 v[10:11], v[8:9], v[28:29] op_sel_hi:[1,0]
	v_cvt_pk_bf16_f32 v8, v16, v17
	v_cvt_pk_bf16_f32 v9, v18, v19
	v_cvt_pk_bf16_f32 v10, v10, v11
	v_cvt_pk_bf16_f32 v11, v24, v25
	global_store_dwordx4 v[30:31], v[8:11], off offset:256
	v_mov_b32_e32 v18, v29
	v_pk_mul_f32 v[14:15], v[14:15], v[18:19] op_sel_hi:[1,0]
	v_add_u32_e32 v8, 0xb0, v160
	v_mad_i64_i32 v[8:9], s[8:9], s8, v8, 0
	v_lshl_add_u64 v[16:17], v[8:9], 1, v[144:145]
	v_pk_mul_f32 v[10:11], v[22:23], v[18:19] op_sel_hi:[1,0]
	v_pk_mul_f32 v[8:9], v[20:21], v[18:19] op_sel_hi:[1,0]
	v_pk_mul_f32 v[12:13], v[12:13], v[18:19] op_sel_hi:[1,0]
	v_cvt_pk_bf16_f32 v8, v8, v9
	v_cvt_pk_bf16_f32 v9, v10, v11
	v_cvt_pk_bf16_f32 v10, v12, v13
	v_cvt_pk_bf16_f32 v11, v14, v15
	global_store_dwordx4 v[16:17], v[8:11], off
	v_pk_mul_f32 v[6:7], v[6:7], v[18:19] op_sel_hi:[1,0]
	v_pk_mul_f32 v[4:5], v[4:5], v[18:19] op_sel_hi:[1,0]
	v_pk_mul_f32 v[8:9], v[2:3], v[18:19] op_sel_hi:[1,0]
	v_pk_mul_f32 v[2:3], v[0:1], v[18:19] op_sel_hi:[1,0]
	v_cvt_pk_bf16_f32 v0, v4, v5
	v_cvt_pk_bf16_f32 v1, v6, v7
	v_cvt_pk_bf16_f32 v2, v2, v3
	v_cvt_pk_bf16_f32 v3, v8, v9
	s_mov_b64 s[8:9], -1
	global_store_dwordx4 v[16:17], v[0:3], off offset:256
	s_cbranch_vccnz .LBB0_149
	s_andn2_b64 vcc, exec, s[0:1]
	s_cbranch_vccnz .LBB0_148
	s_nop 0
	s_branch .LBB0_148
.LBB0_163:
	s_and_b64 vcc, exec, s[6:7]
	s_cbranch_vccz .Lna_G1
	s_barrier

.LBB0_765:
	ds_read_b128 v[144:147], v154
	ds_read_b128 v[162:165], v154 offset:1024
	ds_read_b128 v[166:169], v154 offset:2048
	ds_read_b128 v[170:173], v154 offset:3072
	ds_read_b128 v[174:177], v155
	ds_read_b128 v[178:181], v155 offset:1024
	ds_read_b128 v[182:185], v155 offset:2048
	ds_read_b128 v[186:189], v155 offset:3072
	s_add_u32 s8, s30, 0xfffc0080
	s_addc_u32 s9, s31, -1
	s_cmp_eq_u32 s60, 12
	s_cselect_b32 s37, s15, s9
	s_cselect_b32 s36, s47, s8
	s_cselect_b32 s9, s13, s59
	s_cselect_b32 s8, s55, s58
	v_lshl_add_u64 v[148:149], s[30:31], 0, v[136:137]
	s_add_i32 m0, s4, 0xc000
	ds_read_b128 v[190:193], v156
	ds_read_b128 v[198:201], v156 offset:1024
	ds_read_b128 v[202:205], v156 offset:2048
	ds_read_b128 v[206:209], v156 offset:3072
	ds_read_b128 v[210:213], v156 offset:4096
	ds_read_b128 v[214:217], v156 offset:5120
	ds_read_b128 v[218:221], v156 offset:6144
	ds_read_b128 v[222:225], v156 offset:7168
	global_load_lds_dwordx4 v[148:149], off
	v_lshl_add_u64 v[148:149], s[30:31], 0, v[138:139]
	s_add_i32 m0, s4, 0xe000
	s_nop 0
	global_load_lds_dwordx4 v[148:149], off
	s_waitcnt vmcnt(8)
	s_waitcnt lgkmcnt(0)
	s_barrier
	s_setprio 1
	s_waitcnt lgkmcnt(0)
	v_mfma_f32_16x16x32_bf16 v[124:127], v[144:147], v[190:193], v[124:127]
	v_mfma_f32_16x16x32_bf16 v[120:123], v[166:169], v[190:193], v[120:123]
	v_mfma_f32_16x16x32_bf16 v[108:111], v[144:147], v[202:205], v[108:111]
	v_mfma_f32_16x16x32_bf16 v[104:107], v[166:169], v[202:205], v[104:107]
	v_mfma_f32_16x16x32_bf16 v[92:95], v[144:147], v[210:213], v[92:95]
	v_mfma_f32_16x16x32_bf16 v[88:91], v[166:169], v[210:213], v[88:91]
	v_mfma_f32_16x16x32_bf16 v[76:79], v[144:147], v[218:221], v[76:79]
	v_mfma_f32_16x16x32_bf16 v[72:75], v[166:169], v[218:221], v[72:75]
	v_mfma_f32_16x16x32_bf16 v[124:127], v[162:165], v[198:201], v[124:127]
	v_mfma_f32_16x16x32_bf16 v[120:123], v[170:173], v[198:201], v[120:123]
	v_mfma_f32_16x16x32_bf16 v[108:111], v[162:165], v[206:209], v[108:111]
	v_mfma_f32_16x16x32_bf16 v[104:107], v[170:173], v[206:209], v[104:107]
	v_mfma_f32_16x16x32_bf16 v[92:95], v[162:165], v[214:217], v[92:95]
	v_mfma_f32_16x16x32_bf16 v[88:91], v[170:173], v[214:217], v[88:91]
	v_mfma_f32_16x16x32_bf16 v[76:79], v[162:165], v[222:225], v[76:79]
	v_mfma_f32_16x16x32_bf16 v[72:75], v[170:173], v[222:225], v[72:75]
	s_setprio 0
	s_setprio 1
	v_mfma_f32_16x16x32_bf16 v[116:119], v[174:177], v[190:193], v[116:119]
	v_mfma_f32_16x16x32_bf16 v[112:115], v[182:185], v[190:193], v[112:115]
	v_mfma_f32_16x16x32_bf16 v[100:103], v[174:177], v[202:205], v[100:103]
	v_mfma_f32_16x16x32_bf16 v[96:99], v[182:185], v[202:205], v[96:99]
	v_mfma_f32_16x16x32_bf16 v[84:87], v[174:177], v[210:213], v[84:87]
	v_mfma_f32_16x16x32_bf16 v[80:83], v[182:185], v[210:213], v[80:83]
	v_mfma_f32_16x16x32_bf16 v[68:71], v[174:177], v[218:221], v[68:71]
	v_mfma_f32_16x16x32_bf16 v[64:67], v[182:185], v[218:221], v[64:67]
	v_mfma_f32_16x16x32_bf16 v[116:119], v[178:181], v[198:201], v[116:119]
	v_mfma_f32_16x16x32_bf16 v[112:115], v[186:189], v[198:201], v[112:115]
	v_mfma_f32_16x16x32_bf16 v[100:103], v[178:181], v[206:209], v[100:103]
	v_mfma_f32_16x16x32_bf16 v[96:99], v[186:189], v[206:209], v[96:99]
	v_mfma_f32_16x16x32_bf16 v[84:87], v[178:181], v[214:217], v[84:87]
	v_mfma_f32_16x16x32_bf16 v[80:83], v[186:189], v[214:217], v[80:83]
	v_mfma_f32_16x16x32_bf16 v[68:71], v[178:181], v[222:225], v[68:71]
	v_mfma_f32_16x16x32_bf16 v[64:67], v[186:189], v[222:225], v[64:67]
	s_setprio 0
	s_barrier
	s_add_i32 s61, s38, s3
	v_lshl_add_u64 v[148:149], s[8:9], 0, v[132:133]
	s_mov_b32 m0, s61
	ds_read_b128 v[190:193], v156 offset:16384
	ds_read_b128 v[198:201], v156 offset:17408
	ds_read_b128 v[202:205], v156 offset:18432
	ds_read_b128 v[206:209], v156 offset:19456
	ds_read_b128 v[210:213], v156 offset:20480
	ds_read_b128 v[214:217], v156 offset:21504
	ds_read_b128 v[218:221], v156 offset:22528
	ds_read_b128 v[222:225], v156 offset:23552
	global_load_lds_dwordx4 v[148:149], off
	s_add_i32 m0, s61, 0x2000
	s_add_u32 s64, s8, 0x40000
	v_lshl_add_u64 v[226:227], s[8:9], 0, v[128:129]
	s_addc_u32 s65, s9, 0
	s_add_i32 s61, s39, s3
	global_load_lds_dwordx4 v[226:227], off
	v_lshl_add_u64 v[228:229], s[64:65], 0, v[132:133]
	s_mov_b32 m0, s61
	v_lshl_add_u64 v[230:231], s[36:37], 0, v[130:131]
	global_load_lds_dwordx4 v[228:229], off
	v_lshl_add_u64 v[228:229], s[64:65], 0, v[128:129]
	s_add_i32 m0, s61, 0x2000
	s_nop 0
	global_load_lds_dwordx4 v[228:229], off
	v_lshl_add_u64 v[228:229], s[36:37], 0, v[134:135]
	s_mov_b32 m0, s4
	s_nop 0
	global_load_lds_dwordx4 v[228:229], off
	s_mov_b32 m0, s5
	s_nop 0
	global_load_lds_dwordx4 v[230:231], off
	s_waitcnt vmcnt(8)
	s_waitcnt lgkmcnt(0)
	s_barrier
	s_setprio 1
	s_waitcnt lgkmcnt(0)
	v_mfma_f32_16x16x32_bf16 v[60:63], v[144:147], v[190:193], v[60:63]
	v_mfma_f32_16x16x32_bf16 v[56:59], v[166:169], v[190:193], v[56:59]
	v_mfma_f32_16x16x32_bf16 v[44:47], v[144:147], v[202:205], v[44:47]
	v_mfma_f32_16x16x32_bf16 v[40:43], v[166:169], v[202:205], v[40:43]
	v_mfma_f32_16x16x32_bf16 v[28:31], v[144:147], v[210:213], v[28:31]
	v_mfma_f32_16x16x32_bf16 v[24:27], v[166:169], v[210:213], v[24:27]
	v_mfma_f32_16x16x32_bf16 v[12:15], v[144:147], v[218:221], v[12:15]
	v_mfma_f32_16x16x32_bf16 v[8:11], v[166:169], v[218:221], v[8:11]
	v_mfma_f32_16x16x32_bf16 v[60:63], v[162:165], v[198:201], v[60:63]
	v_mfma_f32_16x16x32_bf16 v[56:59], v[170:173], v[198:201], v[56:59]
	v_mfma_f32_16x16x32_bf16 v[44:47], v[162:165], v[206:209], v[44:47]
	v_mfma_f32_16x16x32_bf16 v[40:43], v[170:173], v[206:209], v[40:43]
	v_mfma_f32_16x16x32_bf16 v[28:31], v[162:165], v[214:217], v[28:31]
	v_mfma_f32_16x16x32_bf16 v[24:27], v[170:173], v[214:217], v[24:27]
	v_mfma_f32_16x16x32_bf16 v[12:15], v[162:165], v[222:225], v[12:15]
	v_mfma_f32_16x16x32_bf16 v[8:11], v[170:173], v[222:225], v[8:11]
	s_setprio 0
	s_setprio 1
	v_mfma_f32_16x16x32_bf16 v[52:55], v[174:177], v[190:193], v[52:55]
	v_mfma_f32_16x16x32_bf16 v[48:51], v[182:185], v[190:193], v[48:51]
	v_mfma_f32_16x16x32_bf16 v[36:39], v[174:177], v[202:205], v[36:39]
	v_mfma_f32_16x16x32_bf16 v[32:35], v[182:185], v[202:205], v[32:35]
	v_mfma_f32_16x16x32_bf16 v[20:23], v[174:177], v[210:213], v[20:23]
	v_mfma_f32_16x16x32_bf16 v[16:19], v[182:185], v[210:213], v[16:19]
	v_mfma_f32_16x16x32_bf16 v[4:7], v[174:177], v[218:221], v[4:7]
	v_mfma_f32_16x16x32_bf16 v[0:3], v[182:185], v[218:221], v[0:3]
	v_mfma_f32_16x16x32_bf16 v[52:55], v[178:181], v[198:201], v[52:55]
	v_mfma_f32_16x16x32_bf16 v[48:51], v[186:189], v[198:201], v[48:51]
	v_mfma_f32_16x16x32_bf16 v[36:39], v[178:181], v[206:209], v[36:39]
	v_mfma_f32_16x16x32_bf16 v[32:35], v[186:189], v[206:209], v[32:35]
	v_mfma_f32_16x16x32_bf16 v[20:23], v[178:181], v[214:217], v[20:23]
	v_mfma_f32_16x16x32_bf16 v[16:19], v[186:189], v[214:217], v[16:19]
	v_mfma_f32_16x16x32_bf16 v[4:7], v[178:181], v[222:225], v[4:7]
	v_mfma_f32_16x16x32_bf16 v[0:3], v[186:189], v[222:225], v[0:3]
	s_setprio 0
	s_barrier
	s_add_i32 s61, 0, 0x18000
	v_add_u32_e32 v157, s61, v151
	s_add_i32 s64, 0, 0x1c000
	ds_read_b128 v[144:147], v157
	ds_read_b128 v[162:165], v157 offset:1024
	ds_read_b128 v[166:169], v157 offset:2048
	ds_read_b128 v[170:173], v157 offset:3072
	v_add_u32_e32 v157, s64, v151
	ds_read_b128 v[174:177], v157
	ds_read_b128 v[178:181], v157 offset:1024
	ds_read_b128 v[182:185], v157 offset:2048
	ds_read_b128 v[186:189], v157 offset:3072
	s_add_u32 s36, s36, 0x40000
	s_addc_u32 s37, s37, 0
	s_mov_b32 m0, s16
	v_lshl_add_u64 v[232:233], s[36:37], 0, v[134:135]
	ds_read_b128 v[190:193], v156 offset:32768
	ds_read_b128 v[198:201], v156 offset:33792
	ds_read_b128 v[202:205], v156 offset:34816
	ds_read_b128 v[206:209], v156 offset:35840
	ds_read_b128 v[210:213], v156 offset:36864
	ds_read_b128 v[214:217], v156 offset:37888
	ds_read_b128 v[218:221], v156 offset:38912
	ds_read_b128 v[222:225], v156 offset:39936
	global_load_lds_dwordx4 v[232:233], off
	v_lshl_add_u64 v[232:233], s[36:37], 0, v[130:131]
	s_mov_b32 m0, s17
	s_nop 0
	global_load_lds_dwordx4 v[232:233], off
	s_waitcnt vmcnt(8)
	s_waitcnt lgkmcnt(0)
	s_barrier
	s_setprio 1
	s_waitcnt lgkmcnt(0)
	v_mfma_f32_16x16x32_bf16 v[124:127], v[144:147], v[190:193], v[124:127]
	v_mfma_f32_16x16x32_bf16 v[120:123], v[166:169], v[190:193], v[120:123]
	v_mfma_f32_16x16x32_bf16 v[108:111], v[144:147], v[202:205], v[108:111]
	v_mfma_f32_16x16x32_bf16 v[104:107], v[166:169], v[202:205], v[104:107]
	v_mfma_f32_16x16x32_bf16 v[92:95], v[144:147], v[210:213], v[92:95]
	v_mfma_f32_16x16x32_bf16 v[88:91], v[166:169], v[210:213], v[88:91]
	v_mfma_f32_16x16x32_bf16 v[76:79], v[144:147], v[218:221], v[76:79]
	v_mfma_f32_16x16x32_bf16 v[72:75], v[166:169], v[218:221], v[72:75]
	v_mfma_f32_16x16x32_bf16 v[124:127], v[162:165], v[198:201], v[124:127]
	v_mfma_f32_16x16x32_bf16 v[120:123], v[170:173], v[198:201], v[120:123]
	v_mfma_f32_16x16x32_bf16 v[108:111], v[162:165], v[206:209], v[108:111]
	v_mfma_f32_16x16x32_bf16 v[104:107], v[170:173], v[206:209], v[104:107]
	v_mfma_f32_16x16x32_bf16 v[92:95], v[162:165], v[214:217], v[92:95]
	v_mfma_f32_16x16x32_bf16 v[88:91], v[170:173], v[214:217], v[88:91]
	v_mfma_f32_16x16x32_bf16 v[76:79], v[162:165], v[222:225], v[76:79]
	v_mfma_f32_16x16x32_bf16 v[72:75], v[170:173], v[222:225], v[72:75]
	s_setprio 0
	s_setprio 1
	v_mfma_f32_16x16x32_bf16 v[116:119], v[174:177], v[190:193], v[116:119]
	v_mfma_f32_16x16x32_bf16 v[112:115], v[182:185], v[190:193], v[112:115]
	v_mfma_f32_16x16x32_bf16 v[100:103], v[174:177], v[202:205], v[100:103]
	v_mfma_f32_16x16x32_bf16 v[96:99], v[182:185], v[202:205], v[96:99]
	v_mfma_f32_16x16x32_bf16 v[84:87], v[174:177], v[210:213], v[84:87]
	v_mfma_f32_16x16x32_bf16 v[80:83], v[182:185], v[210:213], v[80:83]
	v_mfma_f32_16x16x32_bf16 v[68:71], v[174:177], v[218:221], v[68:71]
	v_mfma_f32_16x16x32_bf16 v[64:67], v[182:185], v[218:221], v[64:67]
	v_mfma_f32_16x16x32_bf16 v[116:119], v[178:181], v[198:201], v[116:119]
	v_mfma_f32_16x16x32_bf16 v[112:115], v[186:189], v[198:201], v[112:115]
	v_mfma_f32_16x16x32_bf16 v[100:103], v[178:181], v[206:209], v[100:103]
	v_mfma_f32_16x16x32_bf16 v[96:99], v[186:189], v[206:209], v[96:99]
	v_mfma_f32_16x16x32_bf16 v[84:87], v[178:181], v[214:217], v[84:87]
	v_mfma_f32_16x16x32_bf16 v[80:83], v[186:189], v[214:217], v[80:83]
	v_mfma_f32_16x16x32_bf16 v[68:71], v[178:181], v[222:225], v[68:71]
	v_mfma_f32_16x16x32_bf16 v[64:67], v[186:189], v[222:225], v[64:67]
	s_setprio 0
	s_barrier
	s_add_i32 s36, s61, s3
	v_lshl_add_u64 v[148:149], v[148:149], 0, s[6:7]
	s_mov_b32 m0, s36
	ds_read_b128 v[190:193], v156 offset:49152
	ds_read_b128 v[198:201], v156 offset:50176
	ds_read_b128 v[202:205], v156 offset:51200
	ds_read_b128 v[206:209], v156 offset:52224
	ds_read_b128 v[210:213], v156 offset:53248
	ds_read_b128 v[214:217], v156 offset:54272
	ds_read_b128 v[218:221], v156 offset:55296
	ds_read_b128 v[222:225], v156 offset:56320
	global_load_lds_dwordx4 v[148:149], off
	s_add_i32 m0, s36, 0x2000
	s_add_u32 s8, s8, 0x40080
	v_lshl_add_u64 v[148:149], v[226:227], 0, s[6:7]
	s_addc_u32 s9, s9, 0
	s_add_i32 s36, s64, s3
	global_load_lds_dwordx4 v[148:149], off
	v_lshl_add_u64 v[148:149], s[8:9], 0, v[132:133]
	s_mov_b32 m0, s36
	s_nop 0
	global_load_lds_dwordx4 v[148:149], off
	v_lshl_add_u64 v[148:149], s[8:9], 0, v[128:129]
	s_add_i32 m0, s36, 0x2000
	s_nop 0
	global_load_lds_dwordx4 v[148:149], off
	v_lshl_add_u64 v[148:149], v[228:229], 0, s[6:7]
	s_mov_b32 m0, s29
	s_nop 0
	global_load_lds_dwordx4 v[148:149], off
	v_lshl_add_u64 v[148:149], v[230:231], 0, s[6:7]
	s_mov_b32 m0, s33
	s_nop 0
	global_load_lds_dwordx4 v[148:149], off
	s_waitcnt vmcnt(8)
	s_waitcnt lgkmcnt(0)
	s_barrier
	s_setprio 1
	s_waitcnt lgkmcnt(0)
	v_mfma_f32_16x16x32_bf16 v[60:63], v[144:147], v[190:193], v[60:63]
	v_mfma_f32_16x16x32_bf16 v[56:59], v[166:169], v[190:193], v[56:59]
	v_mfma_f32_16x16x32_bf16 v[44:47], v[144:147], v[202:205], v[44:47]
	v_mfma_f32_16x16x32_bf16 v[40:43], v[166:169], v[202:205], v[40:43]
	v_mfma_f32_16x16x32_bf16 v[28:31], v[144:147], v[210:213], v[28:31]
	v_mfma_f32_16x16x32_bf16 v[24:27], v[166:169], v[210:213], v[24:27]
	v_mfma_f32_16x16x32_bf16 v[12:15], v[144:147], v[218:221], v[12:15]
	v_mfma_f32_16x16x32_bf16 v[8:11], v[166:169], v[218:221], v[8:11]
	v_mfma_f32_16x16x32_bf16 v[60:63], v[162:165], v[198:201], v[60:63]
	v_mfma_f32_16x16x32_bf16 v[56:59], v[170:173], v[198:201], v[56:59]
	v_mfma_f32_16x16x32_bf16 v[44:47], v[162:165], v[206:209], v[44:47]
	v_mfma_f32_16x16x32_bf16 v[40:43], v[170:173], v[206:209], v[40:43]
	v_mfma_f32_16x16x32_bf16 v[28:31], v[162:165], v[214:217], v[28:31]
	v_mfma_f32_16x16x32_bf16 v[24:27], v[170:173], v[214:217], v[24:27]
	v_mfma_f32_16x16x32_bf16 v[12:15], v[162:165], v[222:225], v[12:15]
	v_mfma_f32_16x16x32_bf16 v[8:11], v[170:173], v[222:225], v[8:11]
	s_setprio 0
	s_setprio 1
	v_mfma_f32_16x16x32_bf16 v[52:55], v[174:177], v[190:193], v[52:55]
	v_mfma_f32_16x16x32_bf16 v[48:51], v[182:185], v[190:193], v[48:51]
	v_mfma_f32_16x16x32_bf16 v[36:39], v[174:177], v[202:205], v[36:39]
	v_mfma_f32_16x16x32_bf16 v[32:35], v[182:185], v[202:205], v[32:35]
	v_mfma_f32_16x16x32_bf16 v[20:23], v[174:177], v[210:213], v[20:23]
	v_mfma_f32_16x16x32_bf16 v[16:19], v[182:185], v[210:213], v[16:19]
	v_mfma_f32_16x16x32_bf16 v[4:7], v[174:177], v[218:221], v[4:7]
	v_mfma_f32_16x16x32_bf16 v[0:3], v[182:185], v[218:221], v[0:3]
	v_mfma_f32_16x16x32_bf16 v[52:55], v[178:181], v[198:201], v[52:55]
	v_mfma_f32_16x16x32_bf16 v[48:51], v[186:189], v[198:201], v[48:51]
	v_mfma_f32_16x16x32_bf16 v[36:39], v[178:181], v[206:209], v[36:39]
	v_mfma_f32_16x16x32_bf16 v[32:35], v[186:189], v[206:209], v[32:35]
	v_mfma_f32_16x16x32_bf16 v[20:23], v[178:181], v[214:217], v[20:23]
	v_mfma_f32_16x16x32_bf16 v[16:19], v[186:189], v[214:217], v[16:19]
	v_mfma_f32_16x16x32_bf16 v[4:7], v[178:181], v[222:225], v[4:7]
	v_mfma_f32_16x16x32_bf16 v[0:3], v[186:189], v[222:225], v[0:3]
	s_setprio 0
	s_barrier
	s_add_i32 s60, s60, 2
	s_add_u32 s30, s30, 0x100
	s_addc_u32 s31, s31, 0
	s_add_u32 s58, s58, 0x100
	s_addc_u32 s59, s59, 0
	s_cmp_gt_u32 s60, 13
	s_cbranch_scc0 .LBB0_765
	s_and_b64 vcc, exec, s[10:11]
	s_branch .LBB0_768
	s_barrier
.LBB0_768:
	v_lshl_add_u32 v157, s41, 10, v153
	ds_read2_b32 v[162:163], v157 offset1:16
	v_lshl_add_u32 v146, s28, 8, v150
	v_lshl_add_u32 v144, s46, 8, v152
	v_ashrrev_i32_e32 v145, 31, v144
	v_ashrrev_i32_e32 v147, 31, v146
	s_waitcnt lgkmcnt(0)
	v_pk_mul_f32 v[120:121], v[120:121], v[162:163] op_sel_hi:[1,0]
	v_pk_mul_f32 v[126:127], v[126:127], v[162:163] op_sel_hi:[1,0]
	v_pk_mul_f32 v[124:125], v[124:125], v[162:163] op_sel_hi:[1,0]
	v_pk_mul_f32 v[122:123], v[122:123], v[162:163] op_sel_hi:[1,0]
	v_max_f32_e32 v120, 0, v120
	v_max_f32_e32 v121, 0, v121
	v_max_f32_e32 v124, 0, v124
	v_max_f32_e32 v125, 0, v125
	v_pk_mul_f32 v[164:165], v[120:121], v[120:121]
	v_max_f32_e32 v120, 0, v126
	v_max_f32_e32 v122, 0, v122
	v_max_f32_e32 v121, 0, v127
	v_max_f32_e32 v123, 0, v123
	v_lshl_add_u64 v[148:149], v[144:145], 1, s[18:19]
	v_lshlrev_b64 v[144:145], 13, v[146:147]
	v_pk_mul_f32 v[124:125], v[124:125], v[124:125]
	v_pk_mul_f32 v[126:127], v[120:121], v[120:121]
	v_pk_mul_f32 v[166:167], v[122:123], v[122:123]
	v_pk_mul_f32 v[112:113], v[112:113], v[162:163] op_sel_hi:[1,0]
	v_lshl_add_u64 v[144:145], v[148:149], 0, v[144:145]
	v_cvt_pk_bf16_f32 v120, v124, v125
	v_cvt_pk_bf16_f32 v121, v126, v127
	v_cvt_pk_bf16_f32 v122, v164, v165
	v_cvt_pk_bf16_f32 v123, v166, v167
	v_pk_mul_f32 v[118:119], v[118:119], v[162:163] op_sel_hi:[1,0]
	v_pk_mul_f32 v[116:117], v[116:117], v[162:163] op_sel_hi:[1,0]
	v_pk_mul_f32 v[114:115], v[114:115], v[162:163] op_sel_hi:[1,0]
	v_max_f32_e32 v112, 0, v112
	v_max_f32_e32 v113, 0, v113
	global_store_dwordx4 v[144:145], v[120:123], off
	v_max_f32_e32 v116, 0, v116
	v_max_f32_e32 v117, 0, v117
	v_pk_mul_f32 v[120:121], v[112:113], v[112:113]
	v_max_f32_e32 v112, 0, v118
	v_max_f32_e32 v114, 0, v114
	v_max_f32_e32 v113, 0, v119
	v_max_f32_e32 v115, 0, v115
	v_pk_mul_f32 v[116:117], v[116:117], v[116:117]
	v_pk_mul_f32 v[118:119], v[112:113], v[112:113]
	v_pk_mul_f32 v[122:123], v[114:115], v[114:115]
	v_cvt_pk_bf16_f32 v112, v116, v117
	v_cvt_pk_bf16_f32 v113, v118, v119
	v_cvt_pk_bf16_f32 v114, v120, v121
	v_cvt_pk_bf16_f32 v115, v122, v123
	global_store_dwordx4 v[144:145], v[112:115], off offset:256
	s_mov_b64 s[8:9], 0x100000
	s_nop 0
	v_mov_b32_e32 v114, v163
	v_pk_mul_f32 v[104:105], v[104:105], v[114:115] op_sel_hi:[1,0]
	v_or_b32_e32 v112, 16, v146
	v_pk_mul_f32 v[110:111], v[110:111], v[114:115] op_sel_hi:[1,0]
	v_pk_mul_f32 v[108:109], v[108:109], v[114:115] op_sel_hi:[1,0]
	v_pk_mul_f32 v[106:107], v[106:107], v[114:115] op_sel_hi:[1,0]
	v_max_f32_e32 v104, 0, v104
	v_max_f32_e32 v105, 0, v105
	v_ashrrev_i32_e32 v113, 31, v112
	v_max_f32_e32 v108, 0, v108
	v_max_f32_e32 v109, 0, v109
	v_pk_mul_f32 v[116:117], v[104:105], v[104:105]
	v_max_f32_e32 v104, 0, v110
	v_max_f32_e32 v106, 0, v106
	v_max_f32_e32 v105, 0, v111
	v_max_f32_e32 v107, 0, v107
	v_lshlrev_b64 v[112:113], 13, v[112:113]
	v_pk_mul_f32 v[108:109], v[108:109], v[108:109]
	v_pk_mul_f32 v[110:111], v[104:105], v[104:105]
	v_pk_mul_f32 v[118:119], v[106:107], v[106:107]
	v_pk_mul_f32 v[96:97], v[96:97], v[114:115] op_sel_hi:[1,0]
	v_lshl_add_u64 v[112:113], v[148:149], 0, v[112:113]
	v_cvt_pk_bf16_f32 v104, v108, v109
	v_cvt_pk_bf16_f32 v105, v110, v111
	v_cvt_pk_bf16_f32 v106, v116, v117
	v_cvt_pk_bf16_f32 v107, v118, v119
	v_pk_mul_f32 v[102:103], v[102:103], v[114:115] op_sel_hi:[1,0]
	v_pk_mul_f32 v[100:101], v[100:101], v[114:115] op_sel_hi:[1,0]
	v_pk_mul_f32 v[98:99], v[98:99], v[114:115] op_sel_hi:[1,0]
	v_max_f32_e32 v96, 0, v96
	v_max_f32_e32 v97, 0, v97
	global_store_dwordx4 v[112:113], v[104:107], off
	v_max_f32_e32 v100, 0, v100
	v_max_f32_e32 v101, 0, v101
	v_pk_mul_f32 v[104:105], v[96:97], v[96:97]
	v_max_f32_e32 v96, 0, v102
	v_max_f32_e32 v98, 0, v98
	v_max_f32_e32 v97, 0, v103
	v_max_f32_e32 v99, 0, v99
	v_pk_mul_f32 v[100:101], v[100:101], v[100:101]
	v_pk_mul_f32 v[102:103], v[96:97], v[96:97]
	v_pk_mul_f32 v[106:107], v[98:99], v[98:99]
	v_cvt_pk_bf16_f32 v96, v100, v101
	v_cvt_pk_bf16_f32 v97, v102, v103
	v_cvt_pk_bf16_f32 v98, v104, v105
	v_cvt_pk_bf16_f32 v99, v106, v107
	global_store_dwordx4 v[112:113], v[96:99], off offset:256
	ds_read2_b32 v[96:97], v157 offset0:32 offset1:48
	s_waitcnt lgkmcnt(0)
	v_pk_mul_f32 v[88:89], v[88:89], v[96:97] op_sel_hi:[1,0]
	v_or_b32_e32 v98, 32, v146
	v_pk_mul_f32 v[94:95], v[94:95], v[96:97] op_sel_hi:[1,0]
	v_pk_mul_f32 v[92:93], v[92:93], v[96:97] op_sel_hi:[1,0]
	v_pk_mul_f32 v[90:91], v[90:91], v[96:97] op_sel_hi:[1,0]
	v_max_f32_e32 v88, 0, v88
	v_max_f32_e32 v89, 0, v89
	v_ashrrev_i32_e32 v99, 31, v98
	v_max_f32_e32 v92, 0, v92
	v_max_f32_e32 v93, 0, v93
	v_pk_mul_f32 v[100:101], v[88:89], v[88:89]
	v_max_f32_e32 v88, 0, v94
	v_max_f32_e32 v90, 0, v90
	v_max_f32_e32 v89, 0, v95
	v_max_f32_e32 v91, 0, v91
	v_lshlrev_b64 v[98:99], 13, v[98:99]
	v_pk_mul_f32 v[92:93], v[92:93], v[92:93]
	v_pk_mul_f32 v[94:95], v[88:89], v[88:89]
	v_pk_mul_f32 v[102:103], v[90:91], v[90:91]
	v_pk_mul_f32 v[80:81], v[80:81], v[96:97] op_sel_hi:[1,0]
	v_lshl_add_u64 v[98:99], v[148:149], 0, v[98:99]
	v_cvt_pk_bf16_f32 v88, v92, v93
	v_cvt_pk_bf16_f32 v89, v94, v95
	v_cvt_pk_bf16_f32 v90, v100, v101
	v_cvt_pk_bf16_f32 v91, v102, v103
	v_pk_mul_f32 v[86:87], v[86:87], v[96:97] op_sel_hi:[1,0]
	v_pk_mul_f32 v[84:85], v[84:85], v[96:97] op_sel_hi:[1,0]
	v_pk_mul_f32 v[82:83], v[82:83], v[96:97] op_sel_hi:[1,0]
	v_max_f32_e32 v80, 0, v80
	v_max_f32_e32 v81, 0, v81
	global_store_dwordx4 v[98:99], v[88:91], off
	v_max_f32_e32 v84, 0, v84
	v_max_f32_e32 v85, 0, v85
	v_pk_mul_f32 v[88:89], v[80:81], v[80:81]
	v_max_f32_e32 v80, 0, v86
	v_max_f32_e32 v82, 0, v82
	v_max_f32_e32 v81, 0, v87
	v_max_f32_e32 v83, 0, v83
	v_pk_mul_f32 v[84:85], v[84:85], v[84:85]
	v_pk_mul_f32 v[86:87], v[80:81], v[80:81]
	v_pk_mul_f32 v[90:91], v[82:83], v[82:83]
	v_cvt_pk_bf16_f32 v80, v84, v85
	v_cvt_pk_bf16_f32 v81, v86, v87
	v_cvt_pk_bf16_f32 v82, v88, v89
	v_cvt_pk_bf16_f32 v83, v90, v91
	global_store_dwordx4 v[98:99], v[80:83], off offset:256
	s_nop 1
	v_mov_b32_e32 v82, v97
	v_pk_mul_f32 v[72:73], v[72:73], v[82:83] op_sel_hi:[1,0]
	v_or_b32_e32 v80, 48, v146
	v_pk_mul_f32 v[78:79], v[78:79], v[82:83] op_sel_hi:[1,0]
	v_pk_mul_f32 v[76:77], v[76:77], v[82:83] op_sel_hi:[1,0]
	v_pk_mul_f32 v[74:75], v[74:75], v[82:83] op_sel_hi:[1,0]
	v_max_f32_e32 v72, 0, v72
	v_max_f32_e32 v73, 0, v73
	v_ashrrev_i32_e32 v81, 31, v80
	v_max_f32_e32 v76, 0, v76
	v_max_f32_e32 v77, 0, v77
	v_pk_mul_f32 v[84:85], v[72:73], v[72:73]
	v_max_f32_e32 v72, 0, v78
	v_max_f32_e32 v74, 0, v74
	v_max_f32_e32 v73, 0, v79
	v_max_f32_e32 v75, 0, v75
	v_lshlrev_b64 v[80:81], 13, v[80:81]
	v_pk_mul_f32 v[76:77], v[76:77], v[76:77]
	v_pk_mul_f32 v[78:79], v[72:73], v[72:73]
	v_pk_mul_f32 v[86:87], v[74:75], v[74:75]
	v_pk_mul_f32 v[68:69], v[68:69], v[82:83] op_sel_hi:[1,0]
	v_pk_mul_f32 v[64:65], v[64:65], v[82:83] op_sel_hi:[1,0]
	v_lshl_add_u64 v[80:81], v[148:149], 0, v[80:81]
	v_cvt_pk_bf16_f32 v72, v76, v77
	v_cvt_pk_bf16_f32 v73, v78, v79
	v_cvt_pk_bf16_f32 v74, v84, v85
	v_cvt_pk_bf16_f32 v75, v86, v87
	v_pk_mul_f32 v[70:71], v[70:71], v[82:83] op_sel_hi:[1,0]
	v_max_f32_e32 v68, 0, v68
	v_max_f32_e32 v64, 0, v64
	v_max_f32_e32 v69, 0, v69
	v_max_f32_e32 v65, 0, v65
	global_store_dwordx4 v[80:81], v[72:75], off
	v_pk_mul_f32 v[68:69], v[68:69], v[68:69]
	v_pk_mul_f32 v[66:67], v[66:67], v[82:83] op_sel_hi:[1,0]
	v_pk_mul_f32 v[72:73], v[64:65], v[64:65]
	v_max_f32_e32 v64, 0, v70
	v_max_f32_e32 v65, 0, v71
	v_pk_mul_f32 v[70:71], v[64:65], v[64:65]
	v_cvt_pk_bf16_f32 v64, v68, v69
	ds_read2_b32 v[68:69], v157 offset0:128 offset1:144
	v_max_f32_e32 v66, 0, v66
	v_max_f32_e32 v67, 0, v67
	v_pk_mul_f32 v[74:75], v[66:67], v[66:67]
	v_cvt_pk_bf16_f32 v65, v70, v71
	s_waitcnt lgkmcnt(0)
	v_pk_mul_f32 v[60:61], v[60:61], v[68:69] op_sel_hi:[1,0]
	v_pk_mul_f32 v[56:57], v[56:57], v[68:69] op_sel_hi:[1,0]
	v_cvt_pk_bf16_f32 v66, v72, v73
	v_cvt_pk_bf16_f32 v67, v74, v75
	v_pk_mul_f32 v[62:63], v[62:63], v[68:69] op_sel_hi:[1,0]
	v_pk_mul_f32 v[58:59], v[58:59], v[68:69] op_sel_hi:[1,0]
	v_max_f32_e32 v60, 0, v60
	v_max_f32_e32 v56, 0, v56
	v_max_f32_e32 v61, 0, v61
	v_max_f32_e32 v57, 0, v57
	global_store_dwordx4 v[80:81], v[64:67], off offset:256
	v_pk_mul_f32 v[60:61], v[60:61], v[60:61]
	v_max_f32_e32 v58, 0, v58
	v_lshl_add_u64 v[64:65], v[144:145], 0, s[8:9]
	v_pk_mul_f32 v[66:67], v[56:57], v[56:57]
	v_max_f32_e32 v56, 0, v62
	v_max_f32_e32 v57, 0, v63
	v_max_f32_e32 v59, 0, v59
	s_mov_b32 s8, 0x100000
	v_pk_mul_f32 v[62:63], v[56:57], v[56:57]
	v_pk_mul_f32 v[70:71], v[58:59], v[58:59]
	v_cvt_pk_bf16_f32 v56, v60, v61
	v_add_co_u32_e32 v60, vcc, s8, v144
	v_pk_mul_f32 v[48:49], v[48:49], v[68:69] op_sel_hi:[1,0]
	v_cvt_pk_bf16_f32 v57, v62, v63
	v_cvt_pk_bf16_f32 v58, v66, v67
	v_cvt_pk_bf16_f32 v59, v70, v71
	v_addc_co_u32_e32 v61, vcc, 0, v145, vcc
	v_pk_mul_f32 v[54:55], v[54:55], v[68:69] op_sel_hi:[1,0]
	v_pk_mul_f32 v[52:53], v[52:53], v[68:69] op_sel_hi:[1,0]
	v_pk_mul_f32 v[50:51], v[50:51], v[68:69] op_sel_hi:[1,0]
	v_max_f32_e32 v48, 0, v48
	v_max_f32_e32 v49, 0, v49
	global_store_dwordx4 v[60:61], v[56:59], off
	v_max_f32_e32 v52, 0, v52
	v_max_f32_e32 v53, 0, v53
	v_pk_mul_f32 v[56:57], v[48:49], v[48:49]
	v_max_f32_e32 v48, 0, v54
	v_max_f32_e32 v50, 0, v50
	v_max_f32_e32 v49, 0, v55
	v_max_f32_e32 v51, 0, v51
	v_pk_mul_f32 v[52:53], v[52:53], v[52:53]
	v_pk_mul_f32 v[54:55], v[48:49], v[48:49]
	v_pk_mul_f32 v[58:59], v[50:51], v[50:51]
	v_cvt_pk_bf16_f32 v48, v52, v53
	v_cvt_pk_bf16_f32 v49, v54, v55
	v_cvt_pk_bf16_f32 v50, v56, v57
	v_cvt_pk_bf16_f32 v51, v58, v59
	global_store_dwordx4 v[64:65], v[48:51], off offset:256
	s_mov_b64 s[8:9], 0x120000
	s_nop 0
	v_mov_b32_e32 v50, v69
	v_pk_mul_f32 v[44:45], v[44:45], v[50:51] op_sel_hi:[1,0]
	v_pk_mul_f32 v[40:41], v[40:41], v[50:51] op_sel_hi:[1,0]
	v_pk_mul_f32 v[46:47], v[46:47], v[50:51] op_sel_hi:[1,0]
	v_pk_mul_f32 v[42:43], v[42:43], v[50:51] op_sel_hi:[1,0]
	v_max_f32_e32 v44, 0, v44
	v_max_f32_e32 v40, 0, v40
	v_max_f32_e32 v45, 0, v45
	v_max_f32_e32 v41, 0, v41
	v_lshl_add_u64 v[48:49], v[144:145], 0, s[8:9]
	v_pk_mul_f32 v[44:45], v[44:45], v[44:45]
	v_pk_mul_f32 v[52:53], v[40:41], v[40:41]
	v_max_f32_e32 v40, 0, v46
	v_max_f32_e32 v42, 0, v42
	v_max_f32_e32 v41, 0, v47
	v_max_f32_e32 v43, 0, v43
	s_mov_b32 s8, 0x120000
	v_pk_mul_f32 v[46:47], v[40:41], v[40:41]
	v_pk_mul_f32 v[54:55], v[42:43], v[42:43]
	v_cvt_pk_bf16_f32 v40, v44, v45
	v_add_co_u32_e32 v44, vcc, s8, v144
	v_pk_mul_f32 v[36:37], v[36:37], v[50:51] op_sel_hi:[1,0]
	v_pk_mul_f32 v[32:33], v[32:33], v[50:51] op_sel_hi:[1,0]
	v_cvt_pk_bf16_f32 v41, v46, v47
	v_cvt_pk_bf16_f32 v42, v52, v53
	v_cvt_pk_bf16_f32 v43, v54, v55
	v_addc_co_u32_e32 v45, vcc, 0, v145, vcc
	v_pk_mul_f32 v[38:39], v[38:39], v[50:51] op_sel_hi:[1,0]
	v_max_f32_e32 v36, 0, v36
	v_max_f32_e32 v32, 0, v32
	v_max_f32_e32 v37, 0, v37
	v_max_f32_e32 v33, 0, v33
	global_store_dwordx4 v[44:45], v[40:43], off
	v_pk_mul_f32 v[36:37], v[36:37], v[36:37]
	v_pk_mul_f32 v[34:35], v[34:35], v[50:51] op_sel_hi:[1,0]
	v_pk_mul_f32 v[40:41], v[32:33], v[32:33]
	v_max_f32_e32 v32, 0, v38
	v_max_f32_e32 v33, 0, v39
	v_pk_mul_f32 v[38:39], v[32:33], v[32:33]
	v_cvt_pk_bf16_f32 v32, v36, v37
	ds_read2_b32 v[36:37], v157 offset0:160 offset1:176
	v_max_f32_e32 v34, 0, v34
	v_max_f32_e32 v35, 0, v35
	v_pk_mul_f32 v[42:43], v[34:35], v[34:35]
	v_cvt_pk_bf16_f32 v33, v38, v39
	s_waitcnt lgkmcnt(0)
	v_pk_mul_f32 v[28:29], v[28:29], v[36:37] op_sel_hi:[1,0]
	v_pk_mul_f32 v[24:25], v[24:25], v[36:37] op_sel_hi:[1,0]
	v_cvt_pk_bf16_f32 v34, v40, v41
	v_cvt_pk_bf16_f32 v35, v42, v43
	s_mov_b64 s[8:9], 0x140000
	v_pk_mul_f32 v[30:31], v[30:31], v[36:37] op_sel_hi:[1,0]
	v_pk_mul_f32 v[26:27], v[26:27], v[36:37] op_sel_hi:[1,0]
	v_max_f32_e32 v28, 0, v28
	v_max_f32_e32 v24, 0, v24
	v_max_f32_e32 v29, 0, v29
	v_max_f32_e32 v25, 0, v25
	global_store_dwordx4 v[48:49], v[32:35], off offset:256
	v_pk_mul_f32 v[28:29], v[28:29], v[28:29]
	v_max_f32_e32 v26, 0, v26
	v_lshl_add_u64 v[32:33], v[144:145], 0, s[8:9]
	v_pk_mul_f32 v[34:35], v[24:25], v[24:25]
	v_max_f32_e32 v24, 0, v30
	v_max_f32_e32 v25, 0, v31
	v_max_f32_e32 v27, 0, v27
	s_mov_b32 s8, 0x140000
	v_pk_mul_f32 v[30:31], v[24:25], v[24:25]
	v_pk_mul_f32 v[38:39], v[26:27], v[26:27]
	v_cvt_pk_bf16_f32 v24, v28, v29
	v_add_co_u32_e32 v28, vcc, s8, v144
	v_pk_mul_f32 v[16:17], v[16:17], v[36:37] op_sel_hi:[1,0]
	v_cvt_pk_bf16_f32 v25, v30, v31
	v_cvt_pk_bf16_f32 v26, v34, v35
	v_cvt_pk_bf16_f32 v27, v38, v39
	v_addc_co_u32_e32 v29, vcc, 0, v145, vcc
	v_pk_mul_f32 v[22:23], v[22:23], v[36:37] op_sel_hi:[1,0]
	v_pk_mul_f32 v[20:21], v[20:21], v[36:37] op_sel_hi:[1,0]
	v_pk_mul_f32 v[18:19], v[18:19], v[36:37] op_sel_hi:[1,0]
	v_max_f32_e32 v16, 0, v16
	v_max_f32_e32 v17, 0, v17
	global_store_dwordx4 v[28:29], v[24:27], off
	v_max_f32_e32 v20, 0, v20
	v_max_f32_e32 v21, 0, v21
	v_pk_mul_f32 v[24:25], v[16:17], v[16:17]
	v_max_f32_e32 v16, 0, v22
	v_max_f32_e32 v18, 0, v18
	v_max_f32_e32 v17, 0, v23
	v_max_f32_e32 v19, 0, v19
	v_pk_mul_f32 v[20:21], v[20:21], v[20:21]
	v_pk_mul_f32 v[22:23], v[16:17], v[16:17]
	v_pk_mul_f32 v[26:27], v[18:19], v[18:19]
	v_cvt_pk_bf16_f32 v16, v20, v21
	v_cvt_pk_bf16_f32 v17, v22, v23
	v_cvt_pk_bf16_f32 v18, v24, v25
	v_cvt_pk_bf16_f32 v19, v26, v27
	global_store_dwordx4 v[32:33], v[16:19], off offset:256
	s_mov_b64 s[8:9], 0x160000
	s_nop 0
	v_mov_b32_e32 v18, v37
	v_pk_mul_f32 v[12:13], v[12:13], v[18:19] op_sel_hi:[1,0]
	v_pk_mul_f32 v[8:9], v[8:9], v[18:19] op_sel_hi:[1,0]
	v_pk_mul_f32 v[14:15], v[14:15], v[18:19] op_sel_hi:[1,0]
	v_pk_mul_f32 v[10:11], v[10:11], v[18:19] op_sel_hi:[1,0]
	v_max_f32_e32 v12, 0, v12
	v_max_f32_e32 v8, 0, v8
	v_max_f32_e32 v13, 0, v13
	v_max_f32_e32 v9, 0, v9
	v_lshl_add_u64 v[16:17], v[144:145], 0, s[8:9]
	v_pk_mul_f32 v[12:13], v[12:13], v[12:13]
	v_pk_mul_f32 v[20:21], v[8:9], v[8:9]
	v_max_f32_e32 v8, 0, v14
	v_max_f32_e32 v10, 0, v10
	v_max_f32_e32 v9, 0, v15
	v_max_f32_e32 v11, 0, v11
	s_mov_b32 s8, 0x160000
	v_pk_mul_f32 v[14:15], v[8:9], v[8:9]
	v_pk_mul_f32 v[22:23], v[10:11], v[10:11]
	v_cvt_pk_bf16_f32 v8, v12, v13
	v_add_co_u32_e32 v12, vcc, s8, v144
	v_pk_mul_f32 v[0:1], v[0:1], v[18:19] op_sel_hi:[1,0]
	v_cvt_pk_bf16_f32 v9, v14, v15
	v_cvt_pk_bf16_f32 v10, v20, v21
	v_cvt_pk_bf16_f32 v11, v22, v23
	v_addc_co_u32_e32 v13, vcc, 0, v145, vcc
	v_pk_mul_f32 v[6:7], v[6:7], v[18:19] op_sel_hi:[1,0]
	v_pk_mul_f32 v[4:5], v[4:5], v[18:19] op_sel_hi:[1,0]
	v_pk_mul_f32 v[2:3], v[2:3], v[18:19] op_sel_hi:[1,0]
	v_max_f32_e32 v0, 0, v0
	v_max_f32_e32 v1, 0, v1
	global_store_dwordx4 v[12:13], v[8:11], off
	v_max_f32_e32 v4, 0, v4
	v_max_f32_e32 v5, 0, v5
	v_pk_mul_f32 v[8:9], v[0:1], v[0:1]
	v_max_f32_e32 v0, 0, v6
	v_max_f32_e32 v2, 0, v2
	v_max_f32_e32 v1, 0, v7
	v_max_f32_e32 v3, 0, v3
	v_pk_mul_f32 v[4:5], v[4:5], v[4:5]
	v_pk_mul_f32 v[6:7], v[0:1], v[0:1]
	v_pk_mul_f32 v[10:11], v[2:3], v[2:3]
	v_cvt_pk_bf16_f32 v0, v4, v5
	v_cvt_pk_bf16_f32 v1, v6, v7
	v_cvt_pk_bf16_f32 v2, v8, v9
	v_cvt_pk_bf16_f32 v3, v10, v11
	s_andn2_b64 vcc, exec, s[44:45]
	s_mov_b64 s[8:9], -1
	global_store_dwordx4 v[16:17], v[0:3], off offset:256
	s_cbranch_vccnz .LBB0_757
	s_andn2_b64 vcc, exec, s[0:1]
	s_cbranch_vccnz .LBB0_756
	s_nop 0
	s_branch .LBB0_756
.LBB0_771:
	s_and_b64 vcc, exec, s[10:11]
	s_cbranch_vccz .Lna_G3
	s_barrier

.LBB0_938:
	ds_read_b128 v[146:149], v169
	ds_read_b128 v[150:153], v169 offset:1024
	ds_read_b128 v[154:157], v169 offset:2048
	ds_read_b128 v[174:177], v169 offset:3072
	ds_read_b128 v[178:181], v170
	ds_read_b128 v[182:185], v170 offset:1024
	ds_read_b128 v[186:189], v170 offset:2048
	ds_read_b128 v[190:193], v170 offset:3072
	s_add_u32 s8, s26, 0xfffc0080
	s_addc_u32 s9, s27, -1
	s_cmp_eq_u32 s61, 12
	s_cselect_b32 s29, s15, s9
	s_cselect_b32 s28, s55, s8
	s_cselect_b32 s9, s13, s60
	s_cselect_b32 s8, s58, s59
	v_lshl_add_u64 v[230:231], s[26:27], 0, v[138:139]
	s_add_i32 m0, s5, 0xc000
	ds_read_b128 v[198:201], v171
	ds_read_b128 v[202:205], v171 offset:1024
	ds_read_b128 v[206:209], v171 offset:2048
	ds_read_b128 v[210:213], v171 offset:3072
	ds_read_b128 v[214:217], v171 offset:4096
	ds_read_b128 v[218:221], v171 offset:5120
	ds_read_b128 v[222:225], v171 offset:6144
	ds_read_b128 v[226:229], v171 offset:7168
	global_load_lds_dwordx4 v[230:231], off
	v_lshl_add_u64 v[230:231], s[26:27], 0, v[140:141]
	s_add_i32 m0, s5, 0xe000
	s_nop 0
	global_load_lds_dwordx4 v[230:231], off
	s_waitcnt vmcnt(8)
	s_waitcnt lgkmcnt(0)
	s_barrier
	s_setprio 1
	s_waitcnt lgkmcnt(0)
	v_mfma_f32_16x16x32_bf16 v[124:127], v[146:149], v[198:201], v[124:127]
	v_mfma_f32_16x16x32_bf16 v[120:123], v[154:157], v[198:201], v[120:123]
	v_mfma_f32_16x16x32_bf16 v[116:119], v[146:149], v[206:209], v[116:119]
	v_mfma_f32_16x16x32_bf16 v[108:111], v[154:157], v[206:209], v[108:111]
	v_mfma_f32_16x16x32_bf16 v[100:103], v[146:149], v[214:217], v[100:103]
	v_mfma_f32_16x16x32_bf16 v[92:95], v[154:157], v[214:217], v[92:95]
	v_mfma_f32_16x16x32_bf16 v[84:87], v[146:149], v[222:225], v[84:87]
	v_mfma_f32_16x16x32_bf16 v[76:79], v[154:157], v[222:225], v[76:79]
	v_mfma_f32_16x16x32_bf16 v[124:127], v[150:153], v[202:205], v[124:127]
	v_mfma_f32_16x16x32_bf16 v[120:123], v[174:177], v[202:205], v[120:123]
	v_mfma_f32_16x16x32_bf16 v[116:119], v[150:153], v[210:213], v[116:119]
	v_mfma_f32_16x16x32_bf16 v[108:111], v[174:177], v[210:213], v[108:111]
	v_mfma_f32_16x16x32_bf16 v[100:103], v[150:153], v[218:221], v[100:103]
	v_mfma_f32_16x16x32_bf16 v[92:95], v[174:177], v[218:221], v[92:95]
	v_mfma_f32_16x16x32_bf16 v[84:87], v[150:153], v[226:229], v[84:87]
	v_mfma_f32_16x16x32_bf16 v[76:79], v[174:177], v[226:229], v[76:79]
	s_setprio 0
	s_setprio 1
	v_mfma_f32_16x16x32_bf16 v[112:115], v[178:181], v[198:201], v[112:115]
	v_mfma_f32_16x16x32_bf16 v[104:107], v[186:189], v[198:201], v[104:107]
	v_mfma_f32_16x16x32_bf16 v[96:99], v[178:181], v[206:209], v[96:99]
	v_mfma_f32_16x16x32_bf16 v[88:91], v[186:189], v[206:209], v[88:91]
	v_mfma_f32_16x16x32_bf16 v[80:83], v[178:181], v[214:217], v[80:83]
	v_mfma_f32_16x16x32_bf16 v[72:75], v[186:189], v[214:217], v[72:75]
	v_mfma_f32_16x16x32_bf16 v[68:71], v[178:181], v[222:225], v[68:71]
	v_mfma_f32_16x16x32_bf16 v[64:67], v[186:189], v[222:225], v[64:67]
	v_mfma_f32_16x16x32_bf16 v[112:115], v[182:185], v[202:205], v[112:115]
	v_mfma_f32_16x16x32_bf16 v[104:107], v[190:193], v[202:205], v[104:107]
	v_mfma_f32_16x16x32_bf16 v[96:99], v[182:185], v[210:213], v[96:99]
	v_mfma_f32_16x16x32_bf16 v[88:91], v[190:193], v[210:213], v[88:91]
	v_mfma_f32_16x16x32_bf16 v[80:83], v[182:185], v[218:221], v[80:83]
	v_mfma_f32_16x16x32_bf16 v[72:75], v[190:193], v[218:221], v[72:75]
	v_mfma_f32_16x16x32_bf16 v[68:71], v[182:185], v[226:229], v[68:71]
	v_mfma_f32_16x16x32_bf16 v[64:67], v[190:193], v[226:229], v[64:67]
	s_setprio 0
	s_barrier
	s_add_i32 s62, s37, s3
	v_lshl_add_u64 v[230:231], s[8:9], 0, v[132:133]
	s_mov_b32 m0, s62
	ds_read_b128 v[198:201], v171 offset:16384
	ds_read_b128 v[202:205], v171 offset:17408
	ds_read_b128 v[206:209], v171 offset:18432
	ds_read_b128 v[210:213], v171 offset:19456
	ds_read_b128 v[214:217], v171 offset:20480
	ds_read_b128 v[218:221], v171 offset:21504
	ds_read_b128 v[222:225], v171 offset:22528
	ds_read_b128 v[226:229], v171 offset:23552
	global_load_lds_dwordx4 v[230:231], off
	s_add_i32 m0, s62, 0x2000
	s_add_u32 s62, s8, 0x40000
	v_lshl_add_u64 v[232:233], s[8:9], 0, v[128:129]
	s_addc_u32 s63, s9, 0
	s_add_i32 s64, s38, s3
	global_load_lds_dwordx4 v[232:233], off
	v_lshl_add_u64 v[234:235], s[62:63], 0, v[132:133]
	s_mov_b32 m0, s64
	v_lshl_add_u64 v[236:237], s[28:29], 0, v[130:131]
	global_load_lds_dwordx4 v[234:235], off
	v_lshl_add_u64 v[234:235], s[62:63], 0, v[128:129]
	s_add_i32 m0, s64, 0x2000
	s_nop 0
	global_load_lds_dwordx4 v[234:235], off
	v_lshl_add_u64 v[234:235], s[28:29], 0, v[134:135]
	s_mov_b32 m0, s5
	s_nop 0
	global_load_lds_dwordx4 v[234:235], off
	s_mov_b32 m0, s25
	s_nop 0
	global_load_lds_dwordx4 v[236:237], off
	s_waitcnt vmcnt(8)
	s_waitcnt lgkmcnt(0)
	s_barrier
	s_setprio 1
	s_waitcnt lgkmcnt(0)
	v_mfma_f32_16x16x32_bf16 v[60:63], v[146:149], v[198:201], v[60:63]
	v_mfma_f32_16x16x32_bf16 v[56:59], v[154:157], v[198:201], v[56:59]
	v_mfma_f32_16x16x32_bf16 v[52:55], v[146:149], v[206:209], v[52:55]
	v_mfma_f32_16x16x32_bf16 v[44:47], v[154:157], v[206:209], v[44:47]
	v_mfma_f32_16x16x32_bf16 v[32:35], v[146:149], v[214:217], v[32:35]
	v_mfma_f32_16x16x32_bf16 v[24:27], v[154:157], v[214:217], v[24:27]
	v_mfma_f32_16x16x32_bf16 v[20:23], v[146:149], v[222:225], v[20:23]
	v_mfma_f32_16x16x32_bf16 v[12:15], v[154:157], v[222:225], v[12:15]
	v_mfma_f32_16x16x32_bf16 v[60:63], v[150:153], v[202:205], v[60:63]
	v_mfma_f32_16x16x32_bf16 v[56:59], v[174:177], v[202:205], v[56:59]
	v_mfma_f32_16x16x32_bf16 v[52:55], v[150:153], v[210:213], v[52:55]
	v_mfma_f32_16x16x32_bf16 v[44:47], v[174:177], v[210:213], v[44:47]
	v_mfma_f32_16x16x32_bf16 v[32:35], v[150:153], v[218:221], v[32:35]
	v_mfma_f32_16x16x32_bf16 v[24:27], v[174:177], v[218:221], v[24:27]
	v_mfma_f32_16x16x32_bf16 v[20:23], v[150:153], v[226:229], v[20:23]
	v_mfma_f32_16x16x32_bf16 v[12:15], v[174:177], v[226:229], v[12:15]
	s_setprio 0
	s_setprio 1
	v_mfma_f32_16x16x32_bf16 v[48:51], v[178:181], v[198:201], v[48:51]
	v_mfma_f32_16x16x32_bf16 v[40:43], v[186:189], v[198:201], v[40:43]
	v_mfma_f32_16x16x32_bf16 v[36:39], v[178:181], v[206:209], v[36:39]
	v_mfma_f32_16x16x32_bf16 v[28:31], v[186:189], v[206:209], v[28:31]
	v_mfma_f32_16x16x32_bf16 v[16:19], v[178:181], v[214:217], v[16:19]
	v_mfma_f32_16x16x32_bf16 v[8:11], v[186:189], v[214:217], v[8:11]
	v_mfma_f32_16x16x32_bf16 v[4:7], v[178:181], v[222:225], v[4:7]
	v_mfma_f32_16x16x32_bf16 v[0:3], v[186:189], v[222:225], v[0:3]
	v_mfma_f32_16x16x32_bf16 v[48:51], v[182:185], v[202:205], v[48:51]
	v_mfma_f32_16x16x32_bf16 v[40:43], v[190:193], v[202:205], v[40:43]
	v_mfma_f32_16x16x32_bf16 v[36:39], v[182:185], v[210:213], v[36:39]
	v_mfma_f32_16x16x32_bf16 v[28:31], v[190:193], v[210:213], v[28:31]
	v_mfma_f32_16x16x32_bf16 v[16:19], v[182:185], v[218:221], v[16:19]
	v_mfma_f32_16x16x32_bf16 v[8:11], v[190:193], v[218:221], v[8:11]
	v_mfma_f32_16x16x32_bf16 v[4:7], v[182:185], v[226:229], v[4:7]
	v_mfma_f32_16x16x32_bf16 v[0:3], v[190:193], v[226:229], v[0:3]
	s_setprio 0
	s_barrier
	s_add_i32 s62, 0, 0x18000
	s_add_i32 s63, 0, 0x1c000
	v_add_u32_e32 v174, s62, v162
	v_add_u32_e32 v190, s63, v162
	ds_read_b128 v[146:149], v174
	ds_read_b128 v[150:153], v174 offset:1024
	ds_read_b128 v[154:157], v174 offset:2048
	ds_read_b128 v[174:177], v174 offset:3072
	ds_read_b128 v[178:181], v190
	ds_read_b128 v[182:185], v190 offset:1024
	ds_read_b128 v[186:189], v190 offset:2048
	ds_read_b128 v[190:193], v190 offset:3072
	s_add_u32 s28, s28, 0x40000
	s_addc_u32 s29, s29, 0
	s_mov_b32 m0, s30
	v_lshl_add_u64 v[238:239], s[28:29], 0, v[134:135]
	ds_read_b128 v[198:201], v171 offset:32768
	ds_read_b128 v[202:205], v171 offset:33792
	ds_read_b128 v[206:209], v171 offset:34816
	ds_read_b128 v[210:213], v171 offset:35840
	ds_read_b128 v[214:217], v171 offset:36864
	ds_read_b128 v[218:221], v171 offset:37888
	ds_read_b128 v[222:225], v171 offset:38912
	ds_read_b128 v[226:229], v171 offset:39936
	global_load_lds_dwordx4 v[238:239], off
	v_lshl_add_u64 v[238:239], s[28:29], 0, v[130:131]
	s_mov_b32 m0, s31
	s_nop 0
	global_load_lds_dwordx4 v[238:239], off
	s_waitcnt vmcnt(8)
	s_waitcnt lgkmcnt(0)
	s_barrier
	s_setprio 1
	s_waitcnt lgkmcnt(0)
	v_mfma_f32_16x16x32_bf16 v[124:127], v[146:149], v[198:201], v[124:127]
	v_mfma_f32_16x16x32_bf16 v[120:123], v[154:157], v[198:201], v[120:123]
	v_mfma_f32_16x16x32_bf16 v[116:119], v[146:149], v[206:209], v[116:119]
	v_mfma_f32_16x16x32_bf16 v[108:111], v[154:157], v[206:209], v[108:111]
	v_mfma_f32_16x16x32_bf16 v[100:103], v[146:149], v[214:217], v[100:103]
	v_mfma_f32_16x16x32_bf16 v[92:95], v[154:157], v[214:217], v[92:95]
	v_mfma_f32_16x16x32_bf16 v[84:87], v[146:149], v[222:225], v[84:87]
	v_mfma_f32_16x16x32_bf16 v[76:79], v[154:157], v[222:225], v[76:79]
	v_mfma_f32_16x16x32_bf16 v[124:127], v[150:153], v[202:205], v[124:127]
	v_mfma_f32_16x16x32_bf16 v[120:123], v[174:177], v[202:205], v[120:123]
	v_mfma_f32_16x16x32_bf16 v[116:119], v[150:153], v[210:213], v[116:119]
	v_mfma_f32_16x16x32_bf16 v[108:111], v[174:177], v[210:213], v[108:111]
	v_mfma_f32_16x16x32_bf16 v[100:103], v[150:153], v[218:221], v[100:103]
	v_mfma_f32_16x16x32_bf16 v[92:95], v[174:177], v[218:221], v[92:95]
	v_mfma_f32_16x16x32_bf16 v[84:87], v[150:153], v[226:229], v[84:87]
	v_mfma_f32_16x16x32_bf16 v[76:79], v[174:177], v[226:229], v[76:79]
	s_setprio 0
	s_setprio 1
	v_mfma_f32_16x16x32_bf16 v[112:115], v[178:181], v[198:201], v[112:115]
	v_mfma_f32_16x16x32_bf16 v[104:107], v[186:189], v[198:201], v[104:107]
	v_mfma_f32_16x16x32_bf16 v[96:99], v[178:181], v[206:209], v[96:99]
	v_mfma_f32_16x16x32_bf16 v[88:91], v[186:189], v[206:209], v[88:91]
	v_mfma_f32_16x16x32_bf16 v[80:83], v[178:181], v[214:217], v[80:83]
	v_mfma_f32_16x16x32_bf16 v[72:75], v[186:189], v[214:217], v[72:75]
	v_mfma_f32_16x16x32_bf16 v[68:71], v[178:181], v[222:225], v[68:71]
	v_mfma_f32_16x16x32_bf16 v[64:67], v[186:189], v[222:225], v[64:67]
	v_mfma_f32_16x16x32_bf16 v[112:115], v[182:185], v[202:205], v[112:115]
	v_mfma_f32_16x16x32_bf16 v[104:107], v[190:193], v[202:205], v[104:107]
	v_mfma_f32_16x16x32_bf16 v[96:99], v[182:185], v[210:213], v[96:99]
	v_mfma_f32_16x16x32_bf16 v[88:91], v[190:193], v[210:213], v[88:91]
	v_mfma_f32_16x16x32_bf16 v[80:83], v[182:185], v[218:221], v[80:83]
	v_mfma_f32_16x16x32_bf16 v[72:75], v[190:193], v[218:221], v[72:75]
	v_mfma_f32_16x16x32_bf16 v[68:71], v[182:185], v[226:229], v[68:71]
	v_mfma_f32_16x16x32_bf16 v[64:67], v[190:193], v[226:229], v[64:67]
	s_setprio 0
	s_barrier
	s_add_i32 s28, s62, s3
	v_lshl_add_u64 v[230:231], v[230:231], 0, s[6:7]
	s_mov_b32 m0, s28
	ds_read_b128 v[198:201], v171 offset:49152
	ds_read_b128 v[202:205], v171 offset:50176
	ds_read_b128 v[206:209], v171 offset:51200
	ds_read_b128 v[210:213], v171 offset:52224
	ds_read_b128 v[214:217], v171 offset:53248
	ds_read_b128 v[218:221], v171 offset:54272
	ds_read_b128 v[222:225], v171 offset:55296
	ds_read_b128 v[226:229], v171 offset:56320
	global_load_lds_dwordx4 v[230:231], off
	s_add_i32 m0, s28, 0x2000
	s_add_u32 s8, s8, 0x40080
	v_lshl_add_u64 v[230:231], v[232:233], 0, s[6:7]
	s_addc_u32 s9, s9, 0
	s_add_i32 s28, s63, s3
	global_load_lds_dwordx4 v[230:231], off
	v_lshl_add_u64 v[230:231], s[8:9], 0, v[132:133]
	s_mov_b32 m0, s28
	s_nop 0
	global_load_lds_dwordx4 v[230:231], off
	v_lshl_add_u64 v[230:231], s[8:9], 0, v[128:129]
	s_add_i32 m0, s28, 0x2000
	s_nop 0
	global_load_lds_dwordx4 v[230:231], off
	v_lshl_add_u64 v[230:231], v[234:235], 0, s[6:7]
	s_mov_b32 m0, s33
	s_nop 0
	global_load_lds_dwordx4 v[230:231], off
	v_lshl_add_u64 v[230:231], v[236:237], 0, s[6:7]
	s_mov_b32 m0, s36
	s_nop 0
	global_load_lds_dwordx4 v[230:231], off
	s_waitcnt vmcnt(8)
	s_waitcnt lgkmcnt(0)
	s_barrier
	s_setprio 1
	s_waitcnt lgkmcnt(0)
	v_mfma_f32_16x16x32_bf16 v[60:63], v[146:149], v[198:201], v[60:63]
	v_mfma_f32_16x16x32_bf16 v[56:59], v[154:157], v[198:201], v[56:59]
	v_mfma_f32_16x16x32_bf16 v[52:55], v[146:149], v[206:209], v[52:55]
	v_mfma_f32_16x16x32_bf16 v[44:47], v[154:157], v[206:209], v[44:47]
	v_mfma_f32_16x16x32_bf16 v[32:35], v[146:149], v[214:217], v[32:35]
	v_mfma_f32_16x16x32_bf16 v[24:27], v[154:157], v[214:217], v[24:27]
	v_mfma_f32_16x16x32_bf16 v[20:23], v[146:149], v[222:225], v[20:23]
	v_mfma_f32_16x16x32_bf16 v[12:15], v[154:157], v[222:225], v[12:15]
	v_mfma_f32_16x16x32_bf16 v[60:63], v[150:153], v[202:205], v[60:63]
	v_mfma_f32_16x16x32_bf16 v[56:59], v[174:177], v[202:205], v[56:59]
	v_mfma_f32_16x16x32_bf16 v[52:55], v[150:153], v[210:213], v[52:55]
	v_mfma_f32_16x16x32_bf16 v[44:47], v[174:177], v[210:213], v[44:47]
	v_mfma_f32_16x16x32_bf16 v[32:35], v[150:153], v[218:221], v[32:35]
	v_mfma_f32_16x16x32_bf16 v[24:27], v[174:177], v[218:221], v[24:27]
	v_mfma_f32_16x16x32_bf16 v[20:23], v[150:153], v[226:229], v[20:23]
	v_mfma_f32_16x16x32_bf16 v[12:15], v[174:177], v[226:229], v[12:15]
	s_setprio 0
	s_setprio 1
	v_mfma_f32_16x16x32_bf16 v[48:51], v[178:181], v[198:201], v[48:51]
	v_mfma_f32_16x16x32_bf16 v[40:43], v[186:189], v[198:201], v[40:43]
	v_mfma_f32_16x16x32_bf16 v[36:39], v[178:181], v[206:209], v[36:39]
	v_mfma_f32_16x16x32_bf16 v[28:31], v[186:189], v[206:209], v[28:31]
	v_mfma_f32_16x16x32_bf16 v[16:19], v[178:181], v[214:217], v[16:19]
	v_mfma_f32_16x16x32_bf16 v[8:11], v[186:189], v[214:217], v[8:11]
	v_mfma_f32_16x16x32_bf16 v[4:7], v[178:181], v[222:225], v[4:7]
	v_mfma_f32_16x16x32_bf16 v[0:3], v[186:189], v[222:225], v[0:3]
	v_mfma_f32_16x16x32_bf16 v[48:51], v[182:185], v[202:205], v[48:51]
	v_mfma_f32_16x16x32_bf16 v[40:43], v[190:193], v[202:205], v[40:43]
	v_mfma_f32_16x16x32_bf16 v[36:39], v[182:185], v[210:213], v[36:39]
	v_mfma_f32_16x16x32_bf16 v[28:31], v[190:193], v[210:213], v[28:31]
	v_mfma_f32_16x16x32_bf16 v[16:19], v[182:185], v[218:221], v[16:19]
	v_mfma_f32_16x16x32_bf16 v[8:11], v[190:193], v[218:221], v[8:11]
	v_mfma_f32_16x16x32_bf16 v[4:7], v[182:185], v[226:229], v[4:7]
	v_mfma_f32_16x16x32_bf16 v[0:3], v[190:193], v[226:229], v[0:3]
	s_setprio 0
	s_barrier
	s_add_i32 s61, s61, 2
	s_add_u32 s26, s26, 0x100
	s_addc_u32 s27, s27, 0
	s_add_u32 s59, s59, 0x100
	s_addc_u32 s60, s60, 0
	s_cmp_gt_u32 s61, 13
	s_cbranch_scc0 .LBB0_938
	s_and_b64 vcc, exec, s[10:11]
	s_branch .LBB0_941
	s_barrier

.LBB0_946:
	s_andn2_b64 vcc, exec, s[0:1]
	s_cbranch_vccnz .LBB0_933
	s_nop 0
	s_branch .LBB0_933

.LBB0_1325:
	ds_read_b128 v[144:147], v154
	ds_read_b128 v[158:161], v154 offset:1024
	ds_read_b128 v[162:165], v154 offset:2048
	ds_read_b128 v[166:169], v154 offset:3072
	ds_read_b128 v[170:173], v155
	ds_read_b128 v[174:177], v155 offset:1024
	ds_read_b128 v[178:181], v155 offset:2048
	ds_read_b128 v[182:185], v155 offset:3072
	s_add_u32 s8, s24, 0xfffc0080
	s_addc_u32 s9, s25, -1
	s_cmp_eq_u32 s45, 12
	s_cselect_b32 s27, s15, s9
	s_cselect_b32 s26, s39, s8
	s_cselect_b32 s9, s13, s44
	s_cselect_b32 s8, s40, s41
	v_lshl_add_u64 v[148:149], s[24:25], 0, v[136:137]
	s_add_i32 m0, s4, 0xc000
	ds_read_b128 v[186:189], v156
	ds_read_b128 v[190:193], v156 offset:1024
	ds_read_b128 v[196:199], v156 offset:2048
	ds_read_b128 v[200:203], v156 offset:3072
	ds_read_b128 v[204:207], v156 offset:4096
	ds_read_b128 v[208:211], v156 offset:5120
	ds_read_b128 v[212:215], v156 offset:6144
	ds_read_b128 v[216:219], v156 offset:7168
	global_load_lds_dwordx4 v[148:149], off
	v_lshl_add_u64 v[148:149], s[24:25], 0, v[138:139]
	s_add_i32 m0, s4, 0xe000
	s_nop 0
	global_load_lds_dwordx4 v[148:149], off
	s_waitcnt vmcnt(8)
	s_waitcnt lgkmcnt(0)
	s_barrier
	s_setprio 1
	s_waitcnt lgkmcnt(0)
	v_mfma_f32_16x16x32_bf16 v[124:127], v[144:147], v[186:189], v[124:127]
	v_mfma_f32_16x16x32_bf16 v[120:123], v[162:165], v[186:189], v[120:123]
	v_mfma_f32_16x16x32_bf16 v[108:111], v[144:147], v[196:199], v[108:111]
	v_mfma_f32_16x16x32_bf16 v[104:107], v[162:165], v[196:199], v[104:107]
	v_mfma_f32_16x16x32_bf16 v[92:95], v[144:147], v[204:207], v[92:95]
	v_mfma_f32_16x16x32_bf16 v[88:91], v[162:165], v[204:207], v[88:91]
	v_mfma_f32_16x16x32_bf16 v[76:79], v[144:147], v[212:215], v[76:79]
	v_mfma_f32_16x16x32_bf16 v[72:75], v[162:165], v[212:215], v[72:75]
	v_mfma_f32_16x16x32_bf16 v[124:127], v[158:161], v[190:193], v[124:127]
	v_mfma_f32_16x16x32_bf16 v[120:123], v[166:169], v[190:193], v[120:123]
	v_mfma_f32_16x16x32_bf16 v[108:111], v[158:161], v[200:203], v[108:111]
	v_mfma_f32_16x16x32_bf16 v[104:107], v[166:169], v[200:203], v[104:107]
	v_mfma_f32_16x16x32_bf16 v[92:95], v[158:161], v[208:211], v[92:95]
	v_mfma_f32_16x16x32_bf16 v[88:91], v[166:169], v[208:211], v[88:91]
	v_mfma_f32_16x16x32_bf16 v[76:79], v[158:161], v[216:219], v[76:79]
	v_mfma_f32_16x16x32_bf16 v[72:75], v[166:169], v[216:219], v[72:75]
	s_setprio 0
	s_setprio 1
	v_mfma_f32_16x16x32_bf16 v[116:119], v[170:173], v[186:189], v[116:119]
	v_mfma_f32_16x16x32_bf16 v[112:115], v[178:181], v[186:189], v[112:115]
	v_mfma_f32_16x16x32_bf16 v[100:103], v[170:173], v[196:199], v[100:103]
	v_mfma_f32_16x16x32_bf16 v[96:99], v[178:181], v[196:199], v[96:99]
	v_mfma_f32_16x16x32_bf16 v[84:87], v[170:173], v[204:207], v[84:87]
	v_mfma_f32_16x16x32_bf16 v[80:83], v[178:181], v[204:207], v[80:83]
	v_mfma_f32_16x16x32_bf16 v[68:71], v[170:173], v[212:215], v[68:71]
	v_mfma_f32_16x16x32_bf16 v[64:67], v[178:181], v[212:215], v[64:67]
	v_mfma_f32_16x16x32_bf16 v[116:119], v[174:177], v[190:193], v[116:119]
	v_mfma_f32_16x16x32_bf16 v[112:115], v[182:185], v[190:193], v[112:115]
	v_mfma_f32_16x16x32_bf16 v[100:103], v[174:177], v[200:203], v[100:103]
	v_mfma_f32_16x16x32_bf16 v[96:99], v[182:185], v[200:203], v[96:99]
	v_mfma_f32_16x16x32_bf16 v[84:87], v[174:177], v[208:211], v[84:87]
	v_mfma_f32_16x16x32_bf16 v[80:83], v[182:185], v[208:211], v[80:83]
	v_mfma_f32_16x16x32_bf16 v[68:71], v[174:177], v[216:219], v[68:71]
	v_mfma_f32_16x16x32_bf16 v[64:67], v[182:185], v[216:219], v[64:67]
	s_setprio 0
	s_barrier
	s_add_i32 s46, s31, s3
	v_lshl_add_u64 v[148:149], s[8:9], 0, v[132:133]
	s_mov_b32 m0, s46
	ds_read_b128 v[186:189], v156 offset:16384
	ds_read_b128 v[190:193], v156 offset:17408
	ds_read_b128 v[196:199], v156 offset:18432
	ds_read_b128 v[200:203], v156 offset:19456
	ds_read_b128 v[204:207], v156 offset:20480
	ds_read_b128 v[208:211], v156 offset:21504
	ds_read_b128 v[212:215], v156 offset:22528
	ds_read_b128 v[216:219], v156 offset:23552
	global_load_lds_dwordx4 v[148:149], off
	s_add_i32 m0, s46, 0x2000
	s_add_u32 s46, s8, 0x40000
	v_lshl_add_u64 v[220:221], s[8:9], 0, v[128:129]
	s_addc_u32 s47, s9, 0
	s_add_i32 s50, s33, s3
	global_load_lds_dwordx4 v[220:221], off
	v_lshl_add_u64 v[222:223], s[46:47], 0, v[132:133]
	s_mov_b32 m0, s50
	v_lshl_add_u64 v[224:225], s[26:27], 0, v[130:131]
	global_load_lds_dwordx4 v[222:223], off
	v_lshl_add_u64 v[222:223], s[46:47], 0, v[128:129]
	s_add_i32 m0, s50, 0x2000
	s_nop 0
	global_load_lds_dwordx4 v[222:223], off
	v_lshl_add_u64 v[222:223], s[26:27], 0, v[134:135]
	s_mov_b32 m0, s4
	s_nop 0
	global_load_lds_dwordx4 v[222:223], off
	s_mov_b32 m0, s5
	s_nop 0
	global_load_lds_dwordx4 v[224:225], off
	s_waitcnt vmcnt(8)
	s_waitcnt lgkmcnt(0)
	s_barrier
	s_setprio 1
	s_waitcnt lgkmcnt(0)
	v_mfma_f32_16x16x32_bf16 v[60:63], v[144:147], v[186:189], v[60:63]
	v_mfma_f32_16x16x32_bf16 v[56:59], v[162:165], v[186:189], v[56:59]
	v_mfma_f32_16x16x32_bf16 v[44:47], v[144:147], v[196:199], v[44:47]
	v_mfma_f32_16x16x32_bf16 v[40:43], v[162:165], v[196:199], v[40:43]
	v_mfma_f32_16x16x32_bf16 v[28:31], v[144:147], v[204:207], v[28:31]
	v_mfma_f32_16x16x32_bf16 v[24:27], v[162:165], v[204:207], v[24:27]
	v_mfma_f32_16x16x32_bf16 v[12:15], v[144:147], v[212:215], v[12:15]
	v_mfma_f32_16x16x32_bf16 v[8:11], v[162:165], v[212:215], v[8:11]
	v_mfma_f32_16x16x32_bf16 v[60:63], v[158:161], v[190:193], v[60:63]
	v_mfma_f32_16x16x32_bf16 v[56:59], v[166:169], v[190:193], v[56:59]
	v_mfma_f32_16x16x32_bf16 v[44:47], v[158:161], v[200:203], v[44:47]
	v_mfma_f32_16x16x32_bf16 v[40:43], v[166:169], v[200:203], v[40:43]
	v_mfma_f32_16x16x32_bf16 v[28:31], v[158:161], v[208:211], v[28:31]
	v_mfma_f32_16x16x32_bf16 v[24:27], v[166:169], v[208:211], v[24:27]
	v_mfma_f32_16x16x32_bf16 v[12:15], v[158:161], v[216:219], v[12:15]
	v_mfma_f32_16x16x32_bf16 v[8:11], v[166:169], v[216:219], v[8:11]
	s_setprio 0
	s_setprio 1
	v_mfma_f32_16x16x32_bf16 v[52:55], v[170:173], v[186:189], v[52:55]
	v_mfma_f32_16x16x32_bf16 v[48:51], v[178:181], v[186:189], v[48:51]
	v_mfma_f32_16x16x32_bf16 v[36:39], v[170:173], v[196:199], v[36:39]
	v_mfma_f32_16x16x32_bf16 v[32:35], v[178:181], v[196:199], v[32:35]
	v_mfma_f32_16x16x32_bf16 v[20:23], v[170:173], v[204:207], v[20:23]
	v_mfma_f32_16x16x32_bf16 v[16:19], v[178:181], v[204:207], v[16:19]
	v_mfma_f32_16x16x32_bf16 v[4:7], v[170:173], v[212:215], v[4:7]
	v_mfma_f32_16x16x32_bf16 v[0:3], v[178:181], v[212:215], v[0:3]
	v_mfma_f32_16x16x32_bf16 v[52:55], v[174:177], v[190:193], v[52:55]
	v_mfma_f32_16x16x32_bf16 v[48:51], v[182:185], v[190:193], v[48:51]
	v_mfma_f32_16x16x32_bf16 v[36:39], v[174:177], v[200:203], v[36:39]
	v_mfma_f32_16x16x32_bf16 v[32:35], v[182:185], v[200:203], v[32:35]
	v_mfma_f32_16x16x32_bf16 v[20:23], v[174:177], v[208:211], v[20:23]
	v_mfma_f32_16x16x32_bf16 v[16:19], v[182:185], v[208:211], v[16:19]
	v_mfma_f32_16x16x32_bf16 v[4:7], v[174:177], v[216:219], v[4:7]
	v_mfma_f32_16x16x32_bf16 v[0:3], v[182:185], v[216:219], v[0:3]
	s_setprio 0
	s_barrier
	s_add_i32 s46, 0, 0x18000
	v_add_u32_e32 v157, s46, v151
	s_add_i32 s47, 0, 0x1c000
	ds_read_b128 v[144:147], v157
	ds_read_b128 v[158:161], v157 offset:1024
	ds_read_b128 v[162:165], v157 offset:2048
	ds_read_b128 v[166:169], v157 offset:3072
	v_add_u32_e32 v157, s47, v151
	ds_read_b128 v[170:173], v157
	ds_read_b128 v[174:177], v157 offset:1024
	ds_read_b128 v[178:181], v157 offset:2048
	ds_read_b128 v[182:185], v157 offset:3072
	s_add_u32 s26, s26, 0x40000
	s_addc_u32 s27, s27, 0
	s_mov_b32 m0, s23
	v_lshl_add_u64 v[226:227], s[26:27], 0, v[134:135]
	ds_read_b128 v[186:189], v156 offset:32768
	ds_read_b128 v[190:193], v156 offset:33792
	ds_read_b128 v[196:199], v156 offset:34816
	ds_read_b128 v[200:203], v156 offset:35840
	ds_read_b128 v[204:207], v156 offset:36864
	ds_read_b128 v[208:211], v156 offset:37888
	ds_read_b128 v[212:215], v156 offset:38912
	ds_read_b128 v[216:219], v156 offset:39936
	global_load_lds_dwordx4 v[226:227], off
	v_lshl_add_u64 v[226:227], s[26:27], 0, v[130:131]
	s_mov_b32 m0, s28
	s_nop 0
	global_load_lds_dwordx4 v[226:227], off
	s_waitcnt vmcnt(8)
	s_waitcnt lgkmcnt(0)
	s_barrier
	s_setprio 1
	s_waitcnt lgkmcnt(0)
	v_mfma_f32_16x16x32_bf16 v[124:127], v[144:147], v[186:189], v[124:127]
	v_mfma_f32_16x16x32_bf16 v[120:123], v[162:165], v[186:189], v[120:123]
	v_mfma_f32_16x16x32_bf16 v[108:111], v[144:147], v[196:199], v[108:111]
	v_mfma_f32_16x16x32_bf16 v[104:107], v[162:165], v[196:199], v[104:107]
	v_mfma_f32_16x16x32_bf16 v[92:95], v[144:147], v[204:207], v[92:95]
	v_mfma_f32_16x16x32_bf16 v[88:91], v[162:165], v[204:207], v[88:91]
	v_mfma_f32_16x16x32_bf16 v[76:79], v[144:147], v[212:215], v[76:79]
	v_mfma_f32_16x16x32_bf16 v[72:75], v[162:165], v[212:215], v[72:75]
	v_mfma_f32_16x16x32_bf16 v[124:127], v[158:161], v[190:193], v[124:127]
	v_mfma_f32_16x16x32_bf16 v[120:123], v[166:169], v[190:193], v[120:123]
	v_mfma_f32_16x16x32_bf16 v[108:111], v[158:161], v[200:203], v[108:111]
	v_mfma_f32_16x16x32_bf16 v[104:107], v[166:169], v[200:203], v[104:107]
	v_mfma_f32_16x16x32_bf16 v[92:95], v[158:161], v[208:211], v[92:95]
	v_mfma_f32_16x16x32_bf16 v[88:91], v[166:169], v[208:211], v[88:91]
	v_mfma_f32_16x16x32_bf16 v[76:79], v[158:161], v[216:219], v[76:79]
	v_mfma_f32_16x16x32_bf16 v[72:75], v[166:169], v[216:219], v[72:75]
	s_setprio 0
	s_setprio 1
	v_mfma_f32_16x16x32_bf16 v[116:119], v[170:173], v[186:189], v[116:119]
	v_mfma_f32_16x16x32_bf16 v[112:115], v[178:181], v[186:189], v[112:115]
	v_mfma_f32_16x16x32_bf16 v[100:103], v[170:173], v[196:199], v[100:103]
	v_mfma_f32_16x16x32_bf16 v[96:99], v[178:181], v[196:199], v[96:99]
	v_mfma_f32_16x16x32_bf16 v[84:87], v[170:173], v[204:207], v[84:87]
	v_mfma_f32_16x16x32_bf16 v[80:83], v[178:181], v[204:207], v[80:83]
	v_mfma_f32_16x16x32_bf16 v[68:71], v[170:173], v[212:215], v[68:71]
	v_mfma_f32_16x16x32_bf16 v[64:67], v[178:181], v[212:215], v[64:67]
	v_mfma_f32_16x16x32_bf16 v[116:119], v[174:177], v[190:193], v[116:119]
	v_mfma_f32_16x16x32_bf16 v[112:115], v[182:185], v[190:193], v[112:115]
	v_mfma_f32_16x16x32_bf16 v[100:103], v[174:177], v[200:203], v[100:103]
	v_mfma_f32_16x16x32_bf16 v[96:99], v[182:185], v[200:203], v[96:99]
	v_mfma_f32_16x16x32_bf16 v[84:87], v[174:177], v[208:211], v[84:87]
	v_mfma_f32_16x16x32_bf16 v[80:83], v[182:185], v[208:211], v[80:83]
	v_mfma_f32_16x16x32_bf16 v[68:71], v[174:177], v[216:219], v[68:71]
	v_mfma_f32_16x16x32_bf16 v[64:67], v[182:185], v[216:219], v[64:67]
	s_setprio 0
	s_barrier
	s_add_i32 s26, s46, s3
	v_lshl_add_u64 v[148:149], v[148:149], 0, s[6:7]
	s_mov_b32 m0, s26
	ds_read_b128 v[186:189], v156 offset:49152
	ds_read_b128 v[190:193], v156 offset:50176
	ds_read_b128 v[196:199], v156 offset:51200
	ds_read_b128 v[200:203], v156 offset:52224
	ds_read_b128 v[204:207], v156 offset:53248
	ds_read_b128 v[208:211], v156 offset:54272
	ds_read_b128 v[212:215], v156 offset:55296
	ds_read_b128 v[216:219], v156 offset:56320
	global_load_lds_dwordx4 v[148:149], off
	s_add_i32 m0, s26, 0x2000
	s_add_u32 s8, s8, 0x40080
	v_lshl_add_u64 v[148:149], v[220:221], 0, s[6:7]
	s_addc_u32 s9, s9, 0
	s_add_i32 s26, s47, s3
	global_load_lds_dwordx4 v[148:149], off
	v_lshl_add_u64 v[148:149], s[8:9], 0, v[132:133]
	s_mov_b32 m0, s26
	s_nop 0
	global_load_lds_dwordx4 v[148:149], off
	v_lshl_add_u64 v[148:149], s[8:9], 0, v[128:129]
	s_add_i32 m0, s26, 0x2000
	s_nop 0
	global_load_lds_dwordx4 v[148:149], off
	v_lshl_add_u64 v[148:149], v[222:223], 0, s[6:7]
	s_mov_b32 m0, s29
	s_nop 0
	global_load_lds_dwordx4 v[148:149], off
	v_lshl_add_u64 v[148:149], v[224:225], 0, s[6:7]
	s_mov_b32 m0, s30
	s_nop 0
	global_load_lds_dwordx4 v[148:149], off
	s_waitcnt vmcnt(8)
	s_waitcnt lgkmcnt(0)
	s_barrier
	s_setprio 1
	s_waitcnt lgkmcnt(0)
	v_mfma_f32_16x16x32_bf16 v[60:63], v[144:147], v[186:189], v[60:63]
	v_mfma_f32_16x16x32_bf16 v[56:59], v[162:165], v[186:189], v[56:59]
	v_mfma_f32_16x16x32_bf16 v[44:47], v[144:147], v[196:199], v[44:47]
	v_mfma_f32_16x16x32_bf16 v[40:43], v[162:165], v[196:199], v[40:43]
	v_mfma_f32_16x16x32_bf16 v[28:31], v[144:147], v[204:207], v[28:31]
	v_mfma_f32_16x16x32_bf16 v[24:27], v[162:165], v[204:207], v[24:27]
	v_mfma_f32_16x16x32_bf16 v[12:15], v[144:147], v[212:215], v[12:15]
	v_mfma_f32_16x16x32_bf16 v[8:11], v[162:165], v[212:215], v[8:11]
	v_mfma_f32_16x16x32_bf16 v[60:63], v[158:161], v[190:193], v[60:63]
	v_mfma_f32_16x16x32_bf16 v[56:59], v[166:169], v[190:193], v[56:59]
	v_mfma_f32_16x16x32_bf16 v[44:47], v[158:161], v[200:203], v[44:47]
	v_mfma_f32_16x16x32_bf16 v[40:43], v[166:169], v[200:203], v[40:43]
	v_mfma_f32_16x16x32_bf16 v[28:31], v[158:161], v[208:211], v[28:31]
	v_mfma_f32_16x16x32_bf16 v[24:27], v[166:169], v[208:211], v[24:27]
	v_mfma_f32_16x16x32_bf16 v[12:15], v[158:161], v[216:219], v[12:15]
	v_mfma_f32_16x16x32_bf16 v[8:11], v[166:169], v[216:219], v[8:11]
	s_setprio 0
	s_setprio 1
	v_mfma_f32_16x16x32_bf16 v[52:55], v[170:173], v[186:189], v[52:55]
	v_mfma_f32_16x16x32_bf16 v[48:51], v[178:181], v[186:189], v[48:51]
	v_mfma_f32_16x16x32_bf16 v[36:39], v[170:173], v[196:199], v[36:39]
	v_mfma_f32_16x16x32_bf16 v[32:35], v[178:181], v[196:199], v[32:35]
	v_mfma_f32_16x16x32_bf16 v[20:23], v[170:173], v[204:207], v[20:23]
	v_mfma_f32_16x16x32_bf16 v[16:19], v[178:181], v[204:207], v[16:19]
	v_mfma_f32_16x16x32_bf16 v[4:7], v[170:173], v[212:215], v[4:7]
	v_mfma_f32_16x16x32_bf16 v[0:3], v[178:181], v[212:215], v[0:3]
	v_mfma_f32_16x16x32_bf16 v[52:55], v[174:177], v[190:193], v[52:55]
	v_mfma_f32_16x16x32_bf16 v[48:51], v[182:185], v[190:193], v[48:51]
	v_mfma_f32_16x16x32_bf16 v[36:39], v[174:177], v[200:203], v[36:39]
	v_mfma_f32_16x16x32_bf16 v[32:35], v[182:185], v[200:203], v[32:35]
	v_mfma_f32_16x16x32_bf16 v[20:23], v[174:177], v[208:211], v[20:23]
	v_mfma_f32_16x16x32_bf16 v[16:19], v[182:185], v[208:211], v[16:19]
	v_mfma_f32_16x16x32_bf16 v[4:7], v[174:177], v[216:219], v[4:7]
	v_mfma_f32_16x16x32_bf16 v[0:3], v[182:185], v[216:219], v[0:3]
	s_setprio 0
	s_barrier
	s_add_i32 s45, s45, 2
	s_add_u32 s24, s24, 0x100
	s_addc_u32 s25, s25, 0
	s_add_u32 s41, s41, 0x100
	s_addc_u32 s44, s44, 0
	s_cmp_gt_u32 s45, 13
	s_cbranch_scc0 .LBB0_1325
	s_and_b64 vcc, exec, s[10:11]
	s_branch .LBB0_1328
	s_barrier
.LBB0_1328:
	v_lshl_add_u32 v157, s37, 10, v153
	ds_read2_b32 v[158:159], v157 offset1:16
	v_lshl_add_u32 v146, s22, 8, v150
	v_lshl_add_u32 v144, s38, 8, v152
	v_ashrrev_i32_e32 v145, 31, v144
	v_ashrrev_i32_e32 v147, 31, v146
	s_waitcnt lgkmcnt(0)
	v_pk_mul_f32 v[120:121], v[120:121], v[158:159] op_sel_hi:[1,0]
	v_pk_mul_f32 v[126:127], v[126:127], v[158:159] op_sel_hi:[1,0]
	v_pk_mul_f32 v[124:125], v[124:125], v[158:159] op_sel_hi:[1,0]
	v_pk_mul_f32 v[122:123], v[122:123], v[158:159] op_sel_hi:[1,0]
	v_max_f32_e32 v120, 0, v120
	v_max_f32_e32 v121, 0, v121
	v_max_f32_e32 v124, 0, v124
	v_max_f32_e32 v125, 0, v125
	v_pk_mul_f32 v[160:161], v[120:121], v[120:121]
	v_max_f32_e32 v120, 0, v126
	v_max_f32_e32 v122, 0, v122
	v_max_f32_e32 v121, 0, v127
	v_max_f32_e32 v123, 0, v123
	v_lshl_add_u64 v[148:149], v[144:145], 1, s[18:19]
	v_lshlrev_b64 v[144:145], 13, v[146:147]
	v_pk_mul_f32 v[124:125], v[124:125], v[124:125]
	v_pk_mul_f32 v[126:127], v[120:121], v[120:121]
	v_pk_mul_f32 v[162:163], v[122:123], v[122:123]
	v_pk_mul_f32 v[112:113], v[112:113], v[158:159] op_sel_hi:[1,0]
	v_lshl_add_u64 v[144:145], v[148:149], 0, v[144:145]
	v_cvt_pk_bf16_f32 v120, v124, v125
	v_cvt_pk_bf16_f32 v121, v126, v127
	v_cvt_pk_bf16_f32 v122, v160, v161
	v_cvt_pk_bf16_f32 v123, v162, v163
	v_pk_mul_f32 v[118:119], v[118:119], v[158:159] op_sel_hi:[1,0]
	v_pk_mul_f32 v[116:117], v[116:117], v[158:159] op_sel_hi:[1,0]
	v_pk_mul_f32 v[114:115], v[114:115], v[158:159] op_sel_hi:[1,0]
	v_max_f32_e32 v112, 0, v112
	v_max_f32_e32 v113, 0, v113
	global_store_dwordx4 v[144:145], v[120:123], off
	v_max_f32_e32 v116, 0, v116
	v_max_f32_e32 v117, 0, v117
	v_pk_mul_f32 v[120:121], v[112:113], v[112:113]
	v_max_f32_e32 v112, 0, v118
	v_max_f32_e32 v114, 0, v114
	v_max_f32_e32 v113, 0, v119
	v_max_f32_e32 v115, 0, v115
	v_pk_mul_f32 v[116:117], v[116:117], v[116:117]
	v_pk_mul_f32 v[118:119], v[112:113], v[112:113]
	v_pk_mul_f32 v[122:123], v[114:115], v[114:115]
	v_cvt_pk_bf16_f32 v112, v116, v117
	v_cvt_pk_bf16_f32 v113, v118, v119
	v_cvt_pk_bf16_f32 v114, v120, v121
	v_cvt_pk_bf16_f32 v115, v122, v123
	global_store_dwordx4 v[144:145], v[112:115], off offset:256
	s_mov_b64 s[8:9], 0x100000
	s_nop 0
	v_mov_b32_e32 v114, v159
	v_pk_mul_f32 v[104:105], v[104:105], v[114:115] op_sel_hi:[1,0]
	v_or_b32_e32 v112, 16, v146
	v_pk_mul_f32 v[110:111], v[110:111], v[114:115] op_sel_hi:[1,0]
	v_pk_mul_f32 v[108:109], v[108:109], v[114:115] op_sel_hi:[1,0]
	v_pk_mul_f32 v[106:107], v[106:107], v[114:115] op_sel_hi:[1,0]
	v_max_f32_e32 v104, 0, v104
	v_max_f32_e32 v105, 0, v105
	v_ashrrev_i32_e32 v113, 31, v112
	v_max_f32_e32 v108, 0, v108
	v_max_f32_e32 v109, 0, v109
	v_pk_mul_f32 v[116:117], v[104:105], v[104:105]
	v_max_f32_e32 v104, 0, v110
	v_max_f32_e32 v106, 0, v106
	v_max_f32_e32 v105, 0, v111
	v_max_f32_e32 v107, 0, v107
	v_lshlrev_b64 v[112:113], 13, v[112:113]
	v_pk_mul_f32 v[108:109], v[108:109], v[108:109]
	v_pk_mul_f32 v[110:111], v[104:105], v[104:105]
	v_pk_mul_f32 v[118:119], v[106:107], v[106:107]
	v_pk_mul_f32 v[96:97], v[96:97], v[114:115] op_sel_hi:[1,0]
	v_lshl_add_u64 v[112:113], v[148:149], 0, v[112:113]
	v_cvt_pk_bf16_f32 v104, v108, v109
	v_cvt_pk_bf16_f32 v105, v110, v111
	v_cvt_pk_bf16_f32 v106, v116, v117
	v_cvt_pk_bf16_f32 v107, v118, v119
	v_pk_mul_f32 v[102:103], v[102:103], v[114:115] op_sel_hi:[1,0]
	v_pk_mul_f32 v[100:101], v[100:101], v[114:115] op_sel_hi:[1,0]
	v_pk_mul_f32 v[98:99], v[98:99], v[114:115] op_sel_hi:[1,0]
	v_max_f32_e32 v96, 0, v96
	v_max_f32_e32 v97, 0, v97
	global_store_dwordx4 v[112:113], v[104:107], off
	v_max_f32_e32 v100, 0, v100
	v_max_f32_e32 v101, 0, v101
	v_pk_mul_f32 v[104:105], v[96:97], v[96:97]
	v_max_f32_e32 v96, 0, v102
	v_max_f32_e32 v98, 0, v98
	v_max_f32_e32 v97, 0, v103
	v_max_f32_e32 v99, 0, v99
	v_pk_mul_f32 v[100:101], v[100:101], v[100:101]
	v_pk_mul_f32 v[102:103], v[96:97], v[96:97]
	v_pk_mul_f32 v[106:107], v[98:99], v[98:99]
	v_cvt_pk_bf16_f32 v96, v100, v101
	v_cvt_pk_bf16_f32 v97, v102, v103
	v_cvt_pk_bf16_f32 v98, v104, v105
	v_cvt_pk_bf16_f32 v99, v106, v107
	global_store_dwordx4 v[112:113], v[96:99], off offset:256
	ds_read2_b32 v[96:97], v157 offset0:32 offset1:48
	s_waitcnt lgkmcnt(0)
	v_pk_mul_f32 v[88:89], v[88:89], v[96:97] op_sel_hi:[1,0]
	v_or_b32_e32 v98, 32, v146
	v_pk_mul_f32 v[94:95], v[94:95], v[96:97] op_sel_hi:[1,0]
	v_pk_mul_f32 v[92:93], v[92:93], v[96:97] op_sel_hi:[1,0]
	v_pk_mul_f32 v[90:91], v[90:91], v[96:97] op_sel_hi:[1,0]
	v_max_f32_e32 v88, 0, v88
	v_max_f32_e32 v89, 0, v89
	v_ashrrev_i32_e32 v99, 31, v98
	v_max_f32_e32 v92, 0, v92
	v_max_f32_e32 v93, 0, v93
	v_pk_mul_f32 v[100:101], v[88:89], v[88:89]
	v_max_f32_e32 v88, 0, v94
	v_max_f32_e32 v90, 0, v90
	v_max_f32_e32 v89, 0, v95
	v_max_f32_e32 v91, 0, v91
	v_lshlrev_b64 v[98:99], 13, v[98:99]
	v_pk_mul_f32 v[92:93], v[92:93], v[92:93]
	v_pk_mul_f32 v[94:95], v[88:89], v[88:89]
	v_pk_mul_f32 v[102:103], v[90:91], v[90:91]
	v_pk_mul_f32 v[80:81], v[80:81], v[96:97] op_sel_hi:[1,0]
	v_lshl_add_u64 v[98:99], v[148:149], 0, v[98:99]
	v_cvt_pk_bf16_f32 v88, v92, v93
	v_cvt_pk_bf16_f32 v89, v94, v95
	v_cvt_pk_bf16_f32 v90, v100, v101
	v_cvt_pk_bf16_f32 v91, v102, v103
	v_pk_mul_f32 v[86:87], v[86:87], v[96:97] op_sel_hi:[1,0]
	v_pk_mul_f32 v[84:85], v[84:85], v[96:97] op_sel_hi:[1,0]
	v_pk_mul_f32 v[82:83], v[82:83], v[96:97] op_sel_hi:[1,0]
	v_max_f32_e32 v80, 0, v80
	v_max_f32_e32 v81, 0, v81
	global_store_dwordx4 v[98:99], v[88:91], off
	v_max_f32_e32 v84, 0, v84
	v_max_f32_e32 v85, 0, v85
	v_pk_mul_f32 v[88:89], v[80:81], v[80:81]
	v_max_f32_e32 v80, 0, v86
	v_max_f32_e32 v82, 0, v82
	v_max_f32_e32 v81, 0, v87
	v_max_f32_e32 v83, 0, v83
	v_pk_mul_f32 v[84:85], v[84:85], v[84:85]
	v_pk_mul_f32 v[86:87], v[80:81], v[80:81]
	v_pk_mul_f32 v[90:91], v[82:83], v[82:83]
	v_cvt_pk_bf16_f32 v80, v84, v85
	v_cvt_pk_bf16_f32 v81, v86, v87
	v_cvt_pk_bf16_f32 v82, v88, v89
	v_cvt_pk_bf16_f32 v83, v90, v91
	global_store_dwordx4 v[98:99], v[80:83], off offset:256
	s_nop 1
	v_mov_b32_e32 v82, v97
	v_pk_mul_f32 v[72:73], v[72:73], v[82:83] op_sel_hi:[1,0]
	v_or_b32_e32 v80, 48, v146
	v_pk_mul_f32 v[78:79], v[78:79], v[82:83] op_sel_hi:[1,0]
	v_pk_mul_f32 v[76:77], v[76:77], v[82:83] op_sel_hi:[1,0]
	v_pk_mul_f32 v[74:75], v[74:75], v[82:83] op_sel_hi:[1,0]
	v_max_f32_e32 v72, 0, v72
	v_max_f32_e32 v73, 0, v73
	v_ashrrev_i32_e32 v81, 31, v80
	v_max_f32_e32 v76, 0, v76
	v_max_f32_e32 v77, 0, v77
	v_pk_mul_f32 v[84:85], v[72:73], v[72:73]
	v_max_f32_e32 v72, 0, v78
	v_max_f32_e32 v74, 0, v74
	v_max_f32_e32 v73, 0, v79
	v_max_f32_e32 v75, 0, v75
	v_lshlrev_b64 v[80:81], 13, v[80:81]
	v_pk_mul_f32 v[76:77], v[76:77], v[76:77]
	v_pk_mul_f32 v[78:79], v[72:73], v[72:73]
	v_pk_mul_f32 v[86:87], v[74:75], v[74:75]
	v_pk_mul_f32 v[68:69], v[68:69], v[82:83] op_sel_hi:[1,0]
	v_pk_mul_f32 v[64:65], v[64:65], v[82:83] op_sel_hi:[1,0]
	v_lshl_add_u64 v[80:81], v[148:149], 0, v[80:81]
	v_cvt_pk_bf16_f32 v72, v76, v77
	v_cvt_pk_bf16_f32 v73, v78, v79
	v_cvt_pk_bf16_f32 v74, v84, v85
	v_cvt_pk_bf16_f32 v75, v86, v87
	v_pk_mul_f32 v[70:71], v[70:71], v[82:83] op_sel_hi:[1,0]
	v_max_f32_e32 v68, 0, v68
	v_max_f32_e32 v64, 0, v64
	v_max_f32_e32 v69, 0, v69
	v_max_f32_e32 v65, 0, v65
	global_store_dwordx4 v[80:81], v[72:75], off
	v_pk_mul_f32 v[68:69], v[68:69], v[68:69]
	v_pk_mul_f32 v[66:67], v[66:67], v[82:83] op_sel_hi:[1,0]
	v_pk_mul_f32 v[72:73], v[64:65], v[64:65]
	v_max_f32_e32 v64, 0, v70
	v_max_f32_e32 v65, 0, v71
	v_pk_mul_f32 v[70:71], v[64:65], v[64:65]
	v_cvt_pk_bf16_f32 v64, v68, v69
	ds_read2_b32 v[68:69], v157 offset0:128 offset1:144
	v_max_f32_e32 v66, 0, v66
	v_max_f32_e32 v67, 0, v67
	v_pk_mul_f32 v[74:75], v[66:67], v[66:67]
	v_cvt_pk_bf16_f32 v65, v70, v71
	s_waitcnt lgkmcnt(0)
	v_pk_mul_f32 v[60:61], v[60:61], v[68:69] op_sel_hi:[1,0]
	v_pk_mul_f32 v[56:57], v[56:57], v[68:69] op_sel_hi:[1,0]
	v_cvt_pk_bf16_f32 v66, v72, v73
	v_cvt_pk_bf16_f32 v67, v74, v75
	v_pk_mul_f32 v[62:63], v[62:63], v[68:69] op_sel_hi:[1,0]
	v_pk_mul_f32 v[58:59], v[58:59], v[68:69] op_sel_hi:[1,0]
	v_max_f32_e32 v60, 0, v60
	v_max_f32_e32 v56, 0, v56
	v_max_f32_e32 v61, 0, v61
	v_max_f32_e32 v57, 0, v57
	global_store_dwordx4 v[80:81], v[64:67], off offset:256
	v_pk_mul_f32 v[60:61], v[60:61], v[60:61]
	v_max_f32_e32 v58, 0, v58
	v_lshl_add_u64 v[64:65], v[144:145], 0, s[8:9]
	v_pk_mul_f32 v[66:67], v[56:57], v[56:57]
	v_max_f32_e32 v56, 0, v62
	v_max_f32_e32 v57, 0, v63
	v_max_f32_e32 v59, 0, v59
	s_mov_b32 s8, 0x100000
	v_pk_mul_f32 v[62:63], v[56:57], v[56:57]
	v_pk_mul_f32 v[70:71], v[58:59], v[58:59]
	v_cvt_pk_bf16_f32 v56, v60, v61
	v_add_co_u32_e32 v60, vcc, s8, v144
	v_pk_mul_f32 v[48:49], v[48:49], v[68:69] op_sel_hi:[1,0]
	v_cvt_pk_bf16_f32 v57, v62, v63
	v_cvt_pk_bf16_f32 v58, v66, v67
	v_cvt_pk_bf16_f32 v59, v70, v71
	v_addc_co_u32_e32 v61, vcc, 0, v145, vcc
	v_pk_mul_f32 v[54:55], v[54:55], v[68:69] op_sel_hi:[1,0]
	v_pk_mul_f32 v[52:53], v[52:53], v[68:69] op_sel_hi:[1,0]
	v_pk_mul_f32 v[50:51], v[50:51], v[68:69] op_sel_hi:[1,0]
	v_max_f32_e32 v48, 0, v48
	v_max_f32_e32 v49, 0, v49
	global_store_dwordx4 v[60:61], v[56:59], off
	v_max_f32_e32 v52, 0, v52
	v_max_f32_e32 v53, 0, v53
	v_pk_mul_f32 v[56:57], v[48:49], v[48:49]
	v_max_f32_e32 v48, 0, v54
	v_max_f32_e32 v50, 0, v50
	v_max_f32_e32 v49, 0, v55
	v_max_f32_e32 v51, 0, v51
	v_pk_mul_f32 v[52:53], v[52:53], v[52:53]
	v_pk_mul_f32 v[54:55], v[48:49], v[48:49]
	v_pk_mul_f32 v[58:59], v[50:51], v[50:51]
	v_cvt_pk_bf16_f32 v48, v52, v53
	v_cvt_pk_bf16_f32 v49, v54, v55
	v_cvt_pk_bf16_f32 v50, v56, v57
	v_cvt_pk_bf16_f32 v51, v58, v59
	global_store_dwordx4 v[64:65], v[48:51], off offset:256
	s_mov_b64 s[8:9], 0x120000
	s_nop 0
	v_mov_b32_e32 v50, v69
	v_pk_mul_f32 v[44:45], v[44:45], v[50:51] op_sel_hi:[1,0]
	v_pk_mul_f32 v[40:41], v[40:41], v[50:51] op_sel_hi:[1,0]
	v_pk_mul_f32 v[46:47], v[46:47], v[50:51] op_sel_hi:[1,0]
	v_pk_mul_f32 v[42:43], v[42:43], v[50:51] op_sel_hi:[1,0]
	v_max_f32_e32 v44, 0, v44
	v_max_f32_e32 v40, 0, v40
	v_max_f32_e32 v45, 0, v45
	v_max_f32_e32 v41, 0, v41
	v_lshl_add_u64 v[48:49], v[144:145], 0, s[8:9]
	v_pk_mul_f32 v[44:45], v[44:45], v[44:45]
	v_pk_mul_f32 v[52:53], v[40:41], v[40:41]
	v_max_f32_e32 v40, 0, v46
	v_max_f32_e32 v42, 0, v42
	v_max_f32_e32 v41, 0, v47
	v_max_f32_e32 v43, 0, v43
	s_mov_b32 s8, 0x120000
	v_pk_mul_f32 v[46:47], v[40:41], v[40:41]
	v_pk_mul_f32 v[54:55], v[42:43], v[42:43]
	v_cvt_pk_bf16_f32 v40, v44, v45
	v_add_co_u32_e32 v44, vcc, s8, v144
	v_pk_mul_f32 v[36:37], v[36:37], v[50:51] op_sel_hi:[1,0]
	v_pk_mul_f32 v[32:33], v[32:33], v[50:51] op_sel_hi:[1,0]
	v_cvt_pk_bf16_f32 v41, v46, v47
	v_cvt_pk_bf16_f32 v42, v52, v53
	v_cvt_pk_bf16_f32 v43, v54, v55
	v_addc_co_u32_e32 v45, vcc, 0, v145, vcc
	v_pk_mul_f32 v[38:39], v[38:39], v[50:51] op_sel_hi:[1,0]
	v_max_f32_e32 v36, 0, v36
	v_max_f32_e32 v32, 0, v32
	v_max_f32_e32 v37, 0, v37
	v_max_f32_e32 v33, 0, v33
	global_store_dwordx4 v[44:45], v[40:43], off
	v_pk_mul_f32 v[36:37], v[36:37], v[36:37]
	v_pk_mul_f32 v[34:35], v[34:35], v[50:51] op_sel_hi:[1,0]
	v_pk_mul_f32 v[40:41], v[32:33], v[32:33]
	v_max_f32_e32 v32, 0, v38
	v_max_f32_e32 v33, 0, v39
	v_pk_mul_f32 v[38:39], v[32:33], v[32:33]
	v_cvt_pk_bf16_f32 v32, v36, v37
	ds_read2_b32 v[36:37], v157 offset0:160 offset1:176
	v_max_f32_e32 v34, 0, v34
	v_max_f32_e32 v35, 0, v35
	v_pk_mul_f32 v[42:43], v[34:35], v[34:35]
	v_cvt_pk_bf16_f32 v33, v38, v39
	s_waitcnt lgkmcnt(0)
	v_pk_mul_f32 v[28:29], v[28:29], v[36:37] op_sel_hi:[1,0]
	v_pk_mul_f32 v[24:25], v[24:25], v[36:37] op_sel_hi:[1,0]
	v_cvt_pk_bf16_f32 v34, v40, v41
	v_cvt_pk_bf16_f32 v35, v42, v43
	s_mov_b64 s[8:9], 0x140000
	v_pk_mul_f32 v[30:31], v[30:31], v[36:37] op_sel_hi:[1,0]
	v_pk_mul_f32 v[26:27], v[26:27], v[36:37] op_sel_hi:[1,0]
	v_max_f32_e32 v28, 0, v28
	v_max_f32_e32 v24, 0, v24
	v_max_f32_e32 v29, 0, v29
	v_max_f32_e32 v25, 0, v25
	global_store_dwordx4 v[48:49], v[32:35], off offset:256
	v_pk_mul_f32 v[28:29], v[28:29], v[28:29]
	v_max_f32_e32 v26, 0, v26
	v_lshl_add_u64 v[32:33], v[144:145], 0, s[8:9]
	v_pk_mul_f32 v[34:35], v[24:25], v[24:25]
	v_max_f32_e32 v24, 0, v30
	v_max_f32_e32 v25, 0, v31
	v_max_f32_e32 v27, 0, v27
	s_mov_b32 s8, 0x140000
	v_pk_mul_f32 v[30:31], v[24:25], v[24:25]
	v_pk_mul_f32 v[38:39], v[26:27], v[26:27]
	v_cvt_pk_bf16_f32 v24, v28, v29
	v_add_co_u32_e32 v28, vcc, s8, v144
	v_pk_mul_f32 v[16:17], v[16:17], v[36:37] op_sel_hi:[1,0]
	v_cvt_pk_bf16_f32 v25, v30, v31
	v_cvt_pk_bf16_f32 v26, v34, v35
	v_cvt_pk_bf16_f32 v27, v38, v39
	v_addc_co_u32_e32 v29, vcc, 0, v145, vcc
	v_pk_mul_f32 v[22:23], v[22:23], v[36:37] op_sel_hi:[1,0]
	v_pk_mul_f32 v[20:21], v[20:21], v[36:37] op_sel_hi:[1,0]
	v_pk_mul_f32 v[18:19], v[18:19], v[36:37] op_sel_hi:[1,0]
	v_max_f32_e32 v16, 0, v16
	v_max_f32_e32 v17, 0, v17
	global_store_dwordx4 v[28:29], v[24:27], off
	v_max_f32_e32 v20, 0, v20
	v_max_f32_e32 v21, 0, v21
	v_pk_mul_f32 v[24:25], v[16:17], v[16:17]
	v_max_f32_e32 v16, 0, v22
	v_max_f32_e32 v18, 0, v18
	v_max_f32_e32 v17, 0, v23
	v_max_f32_e32 v19, 0, v19
	v_pk_mul_f32 v[20:21], v[20:21], v[20:21]
	v_pk_mul_f32 v[22:23], v[16:17], v[16:17]
	v_pk_mul_f32 v[26:27], v[18:19], v[18:19]
	v_cvt_pk_bf16_f32 v16, v20, v21
	v_cvt_pk_bf16_f32 v17, v22, v23
	v_cvt_pk_bf16_f32 v18, v24, v25
	v_cvt_pk_bf16_f32 v19, v26, v27
	global_store_dwordx4 v[32:33], v[16:19], off offset:256
	s_mov_b64 s[8:9], 0x160000
	s_nop 0
	v_mov_b32_e32 v18, v37
	v_pk_mul_f32 v[12:13], v[12:13], v[18:19] op_sel_hi:[1,0]
	v_pk_mul_f32 v[8:9], v[8:9], v[18:19] op_sel_hi:[1,0]
	v_pk_mul_f32 v[14:15], v[14:15], v[18:19] op_sel_hi:[1,0]
	v_pk_mul_f32 v[10:11], v[10:11], v[18:19] op_sel_hi:[1,0]
	v_max_f32_e32 v12, 0, v12
	v_max_f32_e32 v8, 0, v8
	v_max_f32_e32 v13, 0, v13
	v_max_f32_e32 v9, 0, v9
	v_lshl_add_u64 v[16:17], v[144:145], 0, s[8:9]
	v_pk_mul_f32 v[12:13], v[12:13], v[12:13]
	v_pk_mul_f32 v[20:21], v[8:9], v[8:9]
	v_max_f32_e32 v8, 0, v14
	v_max_f32_e32 v10, 0, v10
	v_max_f32_e32 v9, 0, v15
	v_max_f32_e32 v11, 0, v11
	s_mov_b32 s8, 0x160000
	v_pk_mul_f32 v[14:15], v[8:9], v[8:9]
	v_pk_mul_f32 v[22:23], v[10:11], v[10:11]
	v_cvt_pk_bf16_f32 v8, v12, v13
	v_add_co_u32_e32 v12, vcc, s8, v144
	v_pk_mul_f32 v[0:1], v[0:1], v[18:19] op_sel_hi:[1,0]
	v_cvt_pk_bf16_f32 v9, v14, v15
	v_cvt_pk_bf16_f32 v10, v20, v21
	v_cvt_pk_bf16_f32 v11, v22, v23
	v_addc_co_u32_e32 v13, vcc, 0, v145, vcc
	v_pk_mul_f32 v[6:7], v[6:7], v[18:19] op_sel_hi:[1,0]
	v_pk_mul_f32 v[4:5], v[4:5], v[18:19] op_sel_hi:[1,0]
	v_pk_mul_f32 v[2:3], v[2:3], v[18:19] op_sel_hi:[1,0]
	v_max_f32_e32 v0, 0, v0
	v_max_f32_e32 v1, 0, v1
	global_store_dwordx4 v[12:13], v[8:11], off
	v_max_f32_e32 v4, 0, v4
	v_max_f32_e32 v5, 0, v5
	v_pk_mul_f32 v[8:9], v[0:1], v[0:1]
	v_max_f32_e32 v0, 0, v6
	v_max_f32_e32 v2, 0, v2
	v_max_f32_e32 v1, 0, v7
	v_max_f32_e32 v3, 0, v3
	v_pk_mul_f32 v[4:5], v[4:5], v[4:5]
	v_pk_mul_f32 v[6:7], v[0:1], v[0:1]
	v_pk_mul_f32 v[10:11], v[2:3], v[2:3]
	v_cvt_pk_bf16_f32 v0, v4, v5
	v_cvt_pk_bf16_f32 v1, v6, v7
	v_cvt_pk_bf16_f32 v2, v8, v9
	v_cvt_pk_bf16_f32 v3, v10, v11
	s_andn2_b64 vcc, exec, s[34:35]
	s_mov_b64 s[8:9], -1
	global_store_dwordx4 v[16:17], v[0:3], off offset:256
	s_cbranch_vccnz .LBB0_1317
	s_andn2_b64 vcc, exec, s[0:1]
	s_cbranch_vccnz .LBB0_1316
	s_nop 0
	s_branch .LBB0_1316
